# sample attention K/V row loads marked nt (streamed once: keep them from displacing the scan / prompt-attention working set in L2)
# speedup vs baseline: 1.0105x; 1.0030x over previous
; __device__ __forceinline__ void p_attn_sample(const float* P, const float* ck, const float* cv, const float* relb, bf16* heads, const float* sbt, unsigned* qctr, volatile LAS unsigned* slot, int wave, int lane_in) {
;     ...
;         __syncthreads(); if (threadIdx.x == 0) *slot = __hip_atomic_fetch_add(qctr, 1u, __ATOMIC_RELAXED, __HIP_MEMORY_SCOPE_AGENT); __syncthreads();
;         const unsigned wt = *slot; if (wt >= (unsigned)(DB * 4)) break;
;         const int b = (int)(wt >> 2), t = wave & 3, h = 2 * (int)(wt & 3u) + (wave >> 2), sr = 4 * b + t, m = MP + sr, p = SEQ + t;
;         f32x4 q0 = *(const f32x4*)(P + (size_t)m * NINP + C_AQ + h * 64 + 8 * c), q1 = *(const f32x4*)(P + (size_t)m * NINP + C_AQ + h * 64 + 8 * c + 4);
;         q0 = q0 * 0.125f; q1 = q1 * 0.125f;
;         const float* knew = P + (size_t)(MP + b * DS) * NINP + C_AK + h * 64 + 8 * c; const float* kold = ck + ((size_t)b * SEQ * NH + h) * HD + 8 * c;
;         const float* vold = cv + ((size_t)b * SEQ * NH + h) * HD + 8 * c;
;         const float* sbh = sbt + h * 392;
;         float mx = -INFINITY, sum = 0.f; float acc[8];
; #pragma unroll
;         for (int j = 0; j < 8; ++j) acc[j] = 0.f;
;         f32x4 ak0[4], ak1[4], av0[4], av1[4], bk0[4], bk1[4], bv0[4], bv1[4]; float ab[4], bbv[4];
;     ...
;         SLOADB(ak0, ak1, av0, av1, ab, 0)
.LBB0_1249:
	s_or_b64 exec, exec, s[0:1]
	v_mov_b32_e32 v2, s29
	s_waitcnt lgkmcnt(0)
	s_barrier
	ds_read_b32 v2, v2
	s_movk_i32 s0, 0x1ff
	s_waitcnt lgkmcnt(0)
	v_cmp_lt_u32_e32 vcc, s0, v2
	v_readfirstlane_b32 s3, v2
	s_mov_b64 s[0:1], -1
	s_cbranch_vccnz .LBB0_1244
	s_lshl_b32 s0, s3, 1
	s_and_b32 s34, s3, 0x1fc
	s_and_b32 s0, s0, 6
	s_or_b32 s2, s34, s27
	s_add_i32 s33, s0, s16
	s_mul_i32 s0, s2, 0x3c00
	s_add_u32 s14, s88, s0
	s_addc_u32 s15, s89, 0
	s_lshl_b32 s22, s33, 6
	s_lshl_b64 s[0:1], s[22:23], 2
	s_add_u32 s14, s14, s0
	s_addc_u32 s15, s15, s1
	v_lshlrev_b32_e32 v156, 1, v154
	s_mulk_i32 s34, 0x3c00
	global_load_dwordx4 v[54:57], v156, s[14:15] offset:128
	global_load_dwordx4 v[62:65], v156, s[14:15]
	s_add_u32 s14, s88, s34
	s_addc_u32 s15, s89, 0
	s_add_u32 s0, s14, s0
	s_addc_u32 s1, s15, s1
	s_lshl_b32 s3, s3, 12
	s_and_b32 s3, s3, 0x1fc000
	s_add_i32 s3, s33, s3
	s_lshl_b32 s14, s3, 6
	s_mov_b32 s15, s23
	s_lshl_b64 s[14:15], s[14:15], 2
	v_lshl_add_u64 v[2:3], s[0:1], 0, v[156:157]
	v_lshl_add_u64 v[194:195], v[158:159], 0, s[14:15]
	v_lshl_add_u64 v[198:199], v[2:3], 0, s[30:31]
	v_lshl_add_u64 v[2:3], v[194:195], 0, v[162:163]
	v_lshl_add_u64 v[4:5], v[198:199], 0, v[164:165]
	v_lshl_add_u64 v[200:201], v[160:161], 0, s[14:15]
	v_cndmask_b32_e64 v3, v3, v5, s[6:7]
	v_cndmask_b32_e64 v2, v2, v4, s[6:7]
	v_lshl_add_u64 v[4:5], v[2:3], 0, s[38:39]
	v_lshl_add_u64 v[6:7], v[200:201], 0, v[186:187]
	v_cndmask_b32_e64 v5, v7, v5, s[6:7]
	v_cndmask_b32_e64 v4, v6, v4, s[6:7]
	global_load_dwordx4 v[14:17], v[2:3], off nt
	global_load_dwordx4 v[10:13], v[2:3], off offset:128 nt
	global_load_dwordx4 v[34:37], v[4:5], off offset:128 nt
	global_load_dwordx4 v[42:45], v[4:5], off nt
	v_lshl_add_u64 v[2:3], v[198:199], 0, v[170:171]
	v_lshl_add_u64 v[4:5], v[194:195], 0, v[168:169]
	v_cndmask_b32_e64 v3, v5, v3, s[8:9]
	v_cndmask_b32_e64 v2, v4, v2, s[8:9]
	v_lshl_add_u64 v[4:5], v[2:3], 0, s[38:39]
	v_lshl_add_u64 v[6:7], v[200:201], 0, v[188:189]
	v_cndmask_b32_e64 v5, v7, v5, s[8:9]
	v_cndmask_b32_e64 v4, v6, v4, s[8:9]
	global_load_dwordx4 v[22:25], v[2:3], off nt
	global_load_dwordx4 v[18:21], v[2:3], off offset:128 nt
	global_load_dwordx4 v[38:41], v[4:5], off offset:128 nt
	global_load_dwordx4 v[50:53], v[4:5], off nt
	v_lshl_add_u64 v[2:3], v[198:199], 0, v[176:177]
	v_lshl_add_u64 v[4:5], v[194:195], 0, v[174:175]
	v_cndmask_b32_e64 v3, v5, v3, s[10:11]
	v_cndmask_b32_e64 v2, v4, v2, s[10:11]
	v_lshl_add_u64 v[4:5], v[2:3], 0, s[38:39]
	v_lshl_add_u64 v[6:7], v[200:201], 0, v[190:191]
	s_mul_i32 s34, s33, 0x188
	s_mov_b32 s35, s23
	v_cndmask_b32_e64 v5, v7, v5, s[10:11]
	v_cndmask_b32_e64 v4, v6, v4, s[10:11]
	s_lshl_b64 s[0:1], s[34:35], 2
	v_readlane_b32 s14, v245, 37
	global_load_dwordx4 v[30:33], v[2:3], off nt
	global_load_dwordx4 v[26:29], v[2:3], off offset:128 nt
	global_load_dwordx4 v[46:49], v[4:5], off offset:128 nt
	global_load_dwordx4 v[58:61], v[4:5], off nt
	v_lshl_add_u64 v[2:3], v[198:199], 0, v[182:183]
	v_lshl_add_u64 v[4:5], v[194:195], 0, v[180:181]
	v_readlane_b32 s15, v245, 38
	s_add_u32 s40, s14, s0
	v_cndmask_b32_e64 v3, v5, v3, s[12:13]
	v_cndmask_b32_e64 v2, v4, v2, s[12:13]
	s_addc_u32 s41, s15, s1
	v_lshl_add_u64 v[4:5], v[2:3], 0, s[38:39]
	v_lshl_add_u64 v[6:7], v[200:201], 0, v[192:193]
	v_lshl_add_u64 v[66:67], v[166:167], 2, s[40:41]
	v_cndmask_b32_e64 v7, v7, v5, s[12:13]
	v_cndmask_b32_e64 v6, v6, v4, s[12:13]
	v_lshl_add_u64 v[68:69], v[172:173], 2, s[40:41]
	v_lshl_add_u64 v[78:79], v[178:179], 2, s[40:41]
	global_load_dwordx4 v[74:77], v[2:3], off nt
	global_load_dwordx4 v[70:73], v[2:3], off offset:128 nt
	s_nop 0
	global_load_dwordx4 v[2:5], v[6:7], off offset:128 nt
	s_nop 0
	global_load_dwordx4 v[6:9], v[6:7], off nt
	v_lshl_add_u64 v[80:81], v[184:185], 2, s[40:41]
	global_load_dword v228, v[66:67], off
	global_load_dword v227, v[68:69], off
	global_load_dword v226, v[78:79], off
	global_load_dword v222, v[80:81], off
	v_mov_b32_e32 v224, 0
	v_mov_b32_e32 v225, 0xff800000
	s_mov_b32 s3, -8
	v_mov_b32_e32 v223, v155
	v_mov_b32_e32 v220, 0
	v_mov_b32_e32 v221, v224
	v_mov_b32_e32 v218, 0
	v_mov_b32_e32 v219, v224
	v_mov_b32_e32 v214, 0
	v_mov_b32_e32 v215, v224
	v_mov_b32_e32 v216, 0
	v_mov_b32_e32 v217, v224
	s_waitcnt vmcnt(0)
	v_pk_mul_f32 v[204:205], v[56:57], s[28:29] op_sel_hi:[1,0]
	v_pk_mul_f32 v[208:209], v[64:65], s[28:29] op_sel_hi:[1,0]
	v_pk_mul_f32 v[206:207], v[62:63], s[28:29] op_sel_hi:[1,0]
	v_pk_mul_f32 v[202:203], v[54:55], s[28:29] op_sel_hi:[1,0]
	v_pk_mov_b32 v[210:211], v[206:207], v[208:209] op_sel:[1,0]
	v_mov_b32_e32 v212, v206
	v_mov_b32_e32 v213, v209
.LBB0_1251:
	v_subrev_u32_e32 v255, 56, v223
	v_min_i32_e32 v255, 0x187, v255
	v_lshl_add_u32 v255, v255, 2, s101
	ds_read_b32 v246, v255
	v_subrev_u32_e32 v255, 48, v223
	v_min_i32_e32 v255, 0x187, v255
	v_lshl_add_u32 v255, v255, 2, s101
	ds_read_b32 v247, v255
	v_subrev_u32_e32 v255, 40, v223
	v_min_i32_e32 v255, 0x187, v255
	v_lshl_add_u32 v255, v255, 2, s101
	ds_read_b32 v248, v255
	v_subrev_u32_e32 v255, 32, v223
	v_min_i32_e32 v255, 0x187, v255
	v_lshl_add_u32 v255, v255, 2, s101
	ds_read_b32 v249, v255
	v_subrev_u32_e32 v255, 24, v223
	v_min_i32_e32 v255, 0x187, v255
	v_lshl_add_u32 v255, v255, 2, s101
	ds_read_b32 v250, v255
	v_subrev_u32_e32 v255, 16, v223
	v_min_i32_e32 v255, 0x187, v255
	v_lshl_add_u32 v255, v255, 2, s101
	ds_read_b32 v251, v255
	v_subrev_u32_e32 v255, 8, v223
	v_min_i32_e32 v255, 0x187, v255
	v_lshl_add_u32 v255, v255, 2, s101
	ds_read_b32 v252, v255
	v_min_i32_e32 v255, 0x187, v223
	v_lshl_add_u32 v255, v255, 2, s101
	ds_read_b32 v253, v255
	s_waitcnt lgkmcnt(0)
	v_subrev_u32_e32 v66, 56, v223
	v_mov_b32_e32 v66, v246
	v_cmp_lt_i32_e32 vcc, s19, v66
	v_min_i32_e32 v54, 0x182, v66
	s_nop 0
	v_cndmask_b32_e64 v55, 0, 1, vcc
	v_cmp_gt_i32_e32 vcc, s24, v66
	s_nop 1
	v_cndmask_b32_e32 v55, 2, v55, vcc
	v_mul_i32_i24_e32 v56, 0xffffff7f, v55
	v_lshlrev_b32_e32 v55, 1, v55
	v_add_lshl_u32 v54, v56, v54, v55
	v_sub_u32_e32 v156, s18, v54
	v_cmp_lt_i32_e32 vcc, s25, v156
	v_cmp_gt_i32_e64 s[0:1], s17, v156
	s_and_saveexec_b64 s[14:15], s[0:1]
	s_xor_b64 s[0:1], exec, s[14:15]
	v_ashrrev_i32_e32 v55, 31, v156
	v_mov_b32_e32 v54, v156
	v_lshlrev_b64 v[56:57], 11, v[54:55]
	v_lshl_add_u64 v[54:55], v[194:195], 0, v[56:57]
	s_andn2_saveexec_b64 s[0:1], s[0:1]
	v_add_u32_e32 v54, 0xfffff800, v156
	v_mad_u64_u32 v[54:55], s[14:15], v54, s26, v[198:199]
	v_lshlrev_b64 v[56:57], 11, v[156:157]
	s_or_b64 exec, exec, s[0:1]
	v_lshl_add_u64 v[62:63], v[54:55], 0, s[38:39]
	v_lshl_add_u64 v[56:57], v[200:201], 0, v[56:57]
	v_cndmask_b32_e32 v63, v57, v63, vcc
	v_cndmask_b32_e32 v62, v56, v62, vcc
	v_min_i32_e32 v66, 0x187, v66
	global_load_dwordx4 v[102:105], v[54:55], off offset:128 nt
	global_load_dwordx4 v[114:117], v[54:55], off nt
	s_nop 0
	global_load_dwordx4 v[54:57], v[62:63], off offset:128 nt
	s_nop 0
	global_load_dwordx4 v[62:65], v[62:63], off nt
	v_ashrrev_i32_e32 v67, 31, v66
	v_lshl_add_u64 v[66:67], v[66:67], 2, s[40:41]
	global_load_dword v229, v[66:67], off
	v_subrev_u32_e32 v82, 48, v223
	v_mov_b32_e32 v82, v247
	v_cmp_lt_i32_e32 vcc, s19, v82
	v_min_i32_e32 v66, 0x182, v82
	s_nop 0
	v_cndmask_b32_e64 v67, 0, 1, vcc
	v_cmp_gt_i32_e32 vcc, s24, v82
	s_nop 1
	v_cndmask_b32_e32 v67, 2, v67, vcc
	v_mul_i32_i24_e32 v68, 0xffffff7f, v67
	v_lshlrev_b32_e32 v67, 1, v67
	v_add_lshl_u32 v66, v68, v66, v67
	v_sub_u32_e32 v68, s18, v66
	v_cmp_lt_i32_e32 vcc, s25, v68
	v_cmp_gt_i32_e64 s[0:1], s17, v68
	s_and_saveexec_b64 s[14:15], s[0:1]
	s_xor_b64 s[0:1], exec, s[14:15]
	v_ashrrev_i32_e32 v69, 31, v68
	v_lshlrev_b64 v[78:79], 11, v[68:69]
	v_lshl_add_u64 v[66:67], v[194:195], 0, v[78:79]
	s_andn2_saveexec_b64 s[0:1], s[0:1]
	v_add_u32_e32 v66, 0xfffff800, v68
	v_mov_b32_e32 v69, v157
	v_mad_u64_u32 v[66:67], s[14:15], v66, s26, v[198:199]
	v_lshlrev_b64 v[78:79], 11, v[68:69]
	s_or_b64 exec, exec, s[0:1]
	v_lshl_add_u64 v[68:69], v[66:67], 0, s[38:39]
	v_lshl_add_u64 v[78:79], v[200:201], 0, v[78:79]
	v_cndmask_b32_e32 v79, v79, v69, vcc
	v_cndmask_b32_e32 v78, v78, v68, vcc
	v_min_i32_e32 v82, 0x187, v82
	global_load_dwordx4 v[118:121], v[66:67], off offset:128 nt
	global_load_dwordx4 v[122:125], v[66:67], off nt
	s_nop 0
	global_load_dwordx4 v[66:69], v[78:79], off offset:128 nt
	s_nop 0
	global_load_dwordx4 v[78:81], v[78:79], off nt
	v_ashrrev_i32_e32 v83, 31, v82
	v_lshl_add_u64 v[82:83], v[82:83], 2, s[40:41]
	global_load_dword v230, v[82:83], off
	v_subrev_u32_e32 v90, 40, v223
	v_mov_b32_e32 v90, v248
	v_cmp_lt_i32_e32 vcc, s19, v90
	v_min_i32_e32 v82, 0x182, v90
	s_nop 0
	v_cndmask_b32_e64 v83, 0, 1, vcc
	v_cmp_gt_i32_e32 vcc, s24, v90
	s_nop 1
	v_cndmask_b32_e32 v83, 2, v83, vcc
	v_mul_i32_i24_e32 v84, 0xffffff7f, v83
	v_lshlrev_b32_e32 v83, 1, v83
	v_add_lshl_u32 v82, v84, v82, v83
	v_sub_u32_e32 v84, s18, v82
	v_cmp_lt_i32_e32 vcc, s25, v84
	v_cmp_gt_i32_e64 s[0:1], s17, v84
	s_and_saveexec_b64 s[14:15], s[0:1]
	s_xor_b64 s[0:1], exec, s[14:15]
	v_ashrrev_i32_e32 v85, 31, v84
	v_lshlrev_b64 v[86:87], 11, v[84:85]
	v_lshl_add_u64 v[82:83], v[194:195], 0, v[86:87]
	s_andn2_saveexec_b64 s[0:1], s[0:1]
	v_add_u32_e32 v82, 0xfffff800, v84
	v_mov_b32_e32 v85, v157
	v_mad_u64_u32 v[82:83], s[14:15], v82, s26, v[198:199]
	v_lshlrev_b64 v[86:87], 11, v[84:85]
	s_or_b64 exec, exec, s[0:1]
	v_lshl_add_u64 v[84:85], v[82:83], 0, s[38:39]
	v_lshl_add_u64 v[86:87], v[200:201], 0, v[86:87]
	v_cndmask_b32_e32 v85, v87, v85, vcc
	v_cndmask_b32_e32 v84, v86, v84, vcc
	global_load_dwordx4 v[134:137], v[82:83], off offset:128 nt
	global_load_dwordx4 v[138:141], v[82:83], off nt
	global_load_dwordx4 v[86:89], v[84:85], off offset:128 nt
	global_load_dwordx4 v[94:97], v[84:85], off nt
	v_min_i32_e32 v82, 0x187, v90
	v_ashrrev_i32_e32 v83, 31, v82
	v_lshl_add_u64 v[82:83], v[82:83], 2, s[40:41]
	global_load_dword v231, v[82:83], off
	v_subrev_u32_e32 v92, 32, v223
	v_mov_b32_e32 v92, v249
	v_cmp_lt_i32_e32 vcc, s19, v92
	v_min_i32_e32 v82, 0x182, v92
	s_nop 0
	v_cndmask_b32_e64 v83, 0, 1, vcc
	v_cmp_gt_i32_e32 vcc, s24, v92
	s_nop 1
	v_cndmask_b32_e32 v83, 2, v83, vcc
	v_mul_i32_i24_e32 v84, 0xffffff7f, v83
	v_lshlrev_b32_e32 v83, 1, v83
	v_add_lshl_u32 v82, v84, v82, v83
	v_sub_u32_e32 v84, s18, v82
	v_cmp_lt_i32_e32 vcc, s25, v84
	v_cmp_gt_i32_e64 s[0:1], s17, v84
	s_and_saveexec_b64 s[14:15], s[0:1]
	s_xor_b64 s[0:1], exec, s[14:15]
	v_ashrrev_i32_e32 v85, 31, v84
	v_lshlrev_b64 v[90:91], 11, v[84:85]
	v_lshl_add_u64 v[82:83], v[194:195], 0, v[90:91]
	s_andn2_saveexec_b64 s[0:1], s[0:1]
	v_add_u32_e32 v82, 0xfffff800, v84
	v_mov_b32_e32 v85, v157
	v_mad_u64_u32 v[82:83], s[14:15], v82, s26, v[198:199]
	v_lshlrev_b64 v[90:91], 11, v[84:85]
	s_or_b64 exec, exec, s[0:1]
	v_lshl_add_u64 v[84:85], v[82:83], 0, s[38:39]
	v_lshl_add_u64 v[90:91], v[200:201], 0, v[90:91]
	v_cndmask_b32_e32 v85, v91, v85, vcc
	v_cndmask_b32_e32 v84, v90, v84, vcc
	global_load_dwordx4 v[142:145], v[82:83], off offset:128 nt
	global_load_dwordx4 v[146:149], v[82:83], off nt
	global_load_dwordx4 v[110:113], v[84:85], off offset:128 nt
	global_load_dwordx4 v[126:129], v[84:85], off nt
	v_min_i32_e32 v82, 0x187, v92
	v_ashrrev_i32_e32 v83, 31, v82
	v_lshl_add_u64 v[82:83], v[82:83], 2, s[40:41]
	global_load_dword v232, v[82:83], off
	v_mov_b32_e32 v82, v15
	v_mov_b32_e32 v15, v17
	v_mov_b32_e32 v83, v16
	v_pk_mul_f32 v[14:15], v[212:213], v[14:15]
	v_pk_mul_f32 v[12:13], v[204:205], v[12:13]
	v_pk_mul_f32 v[10:11], v[202:203], v[10:11]
	v_pk_fma_f32 v[14:15], v[210:211], v[82:83], v[14:15]
	v_mov_b32_e32 v16, v12
	v_mov_b32_e32 v17, v10
	v_mov_b32_e32 v10, v13
	v_pk_add_f32 v[10:11], v[16:17], v[10:11]
	v_add_f32_e32 v12, v14, v15
	v_add_f32_e32 v11, v11, v12
	v_add_f32_e32 v10, v10, v11
	v_mov_b32_e32 v11, v24
	v_pk_mul_f32 v[14:15], v[202:203], v[18:19]
	v_add_f32_dpp v10, v10, v10 quad_perm:[1,0,3,2] row_mask:0xf bank_mask:0xf bound_ctrl:1
	v_mov_b32_e32 v17, v14
	v_subrev_u32_e32 v18, 24, v223
	v_mov_b32_e32 v18, v250
	v_add_f32_dpp v236, v10, v10 quad_perm:[2,3,0,1] row_mask:0xf bank_mask:0xf bound_ctrl:1
	v_mov_b32_e32 v10, v23
	v_mov_b32_e32 v23, v25
	v_pk_mul_f32 v[12:13], v[212:213], v[22:23]
	v_cmp_lt_i32_e32 vcc, s19, v18
	v_pk_fma_f32 v[10:11], v[210:211], v[10:11], v[12:13]
	v_pk_mul_f32 v[12:13], v[204:205], v[20:21]
	v_add_f32_e32 v10, v10, v11
	v_mov_b32_e32 v16, v12
	v_mov_b32_e32 v14, v13
	v_pk_add_f32 v[12:13], v[16:17], v[14:15]
	v_mov_b32_e32 v11, v32
	v_add_f32_e32 v10, v13, v10
	v_add_f32_e32 v10, v12, v10
	v_pk_mul_f32 v[14:15], v[202:203], v[26:27]
	v_mov_b32_e32 v237, 0
	v_add_f32_dpp v10, v10, v10 quad_perm:[1,0,3,2] row_mask:0xf bank_mask:0xf bound_ctrl:1
	v_mov_b32_e32 v17, v14
	v_mov_b32_e32 v239, 0
	v_add_f32_dpp v238, v10, v10 quad_perm:[2,3,0,1] row_mask:0xf bank_mask:0xf bound_ctrl:1
	v_mov_b32_e32 v10, v31
	v_mov_b32_e32 v31, v33
	v_pk_mul_f32 v[12:13], v[212:213], v[30:31]
	v_mov_b32_e32 v241, 0
	v_pk_fma_f32 v[10:11], v[210:211], v[10:11], v[12:13]
	v_pk_mul_f32 v[12:13], v[204:205], v[28:29]
	v_add_f32_e32 v10, v10, v11
	v_mov_b32_e32 v16, v12
	v_mov_b32_e32 v14, v13
	v_pk_add_f32 v[12:13], v[16:17], v[14:15]
	s_waitcnt vmcnt(23)
	v_mov_b32_e32 v11, v76
	v_add_f32_e32 v10, v13, v10
	v_add_f32_e32 v10, v12, v10
	v_pk_mul_f32 v[14:15], v[202:203], v[70:71]
	v_mov_b32_dpp v237, v236 row_half_mirror row_mask:0xf bank_mask:0xf
	v_add_f32_dpp v10, v10, v10 quad_perm:[1,0,3,2] row_mask:0xf bank_mask:0xf bound_ctrl:1
	v_mov_b32_e32 v17, v14
	v_mov_b32_dpp v239, v238 row_half_mirror row_mask:0xf bank_mask:0xf
	v_add_f32_dpp v240, v10, v10 quad_perm:[2,3,0,1] row_mask:0xf bank_mask:0xf bound_ctrl:1
	v_mov_b32_e32 v10, v75
	v_mov_b32_e32 v75, v77
	v_pk_mul_f32 v[12:13], v[212:213], v[74:75]
	v_mov_b32_e32 v77, 0
	v_pk_fma_f32 v[10:11], v[210:211], v[10:11], v[12:13]
	v_pk_mul_f32 v[12:13], v[204:205], v[72:73]
	v_add_f32_e32 v10, v10, v11
	v_mov_b32_e32 v16, v12
	v_mov_b32_e32 v14, v13
	v_pk_add_f32 v[12:13], v[16:17], v[14:15]
	v_cndmask_b32_e64 v11, 0, 1, vcc
	v_add_f32_e32 v10, v13, v10
	v_add_f32_e32 v10, v12, v10
	v_cmp_gt_i32_e32 vcc, s24, v18
	v_mov_b32_dpp v241, v240 row_half_mirror row_mask:0xf bank_mask:0xf
	v_add_f32_dpp v10, v10, v10 quad_perm:[1,0,3,2] row_mask:0xf bank_mask:0xf bound_ctrl:1
	v_cndmask_b32_e32 v11, 2, v11, vcc
	v_mul_i32_i24_e32 v12, 0xffffff7f, v11
	v_add_f32_dpp v76, v10, v10 quad_perm:[2,3,0,1] row_mask:0xf bank_mask:0xf bound_ctrl:1
	v_min_i32_e32 v10, 0x182, v18
	v_lshlrev_b32_e32 v11, 1, v11
	v_add_lshl_u32 v10, v12, v10, v11
	v_sub_u32_e32 v156, s18, v10
	v_mov_b32_dpp v77, v76 row_half_mirror row_mask:0xf bank_mask:0xf
	v_cmp_lt_i32_e32 vcc, s25, v156
	v_cmp_gt_i32_e64 s[0:1], s17, v156
	s_and_saveexec_b64 s[14:15], s[0:1]
	s_xor_b64 s[0:1], exec, s[14:15]
	v_ashrrev_i32_e32 v11, 31, v156
	v_mov_b32_e32 v10, v156
	v_lshlrev_b64 v[10:11], 11, v[10:11]
	v_lshl_add_u64 v[14:15], v[194:195], 0, v[10:11]
	s_andn2_saveexec_b64 s[0:1], s[0:1]
	v_add_u32_e32 v10, 0xfffff800, v156
	v_mad_u64_u32 v[14:15], s[14:15], v10, s26, v[198:199]
	v_lshlrev_b64 v[10:11], 11, v[156:157]
	s_or_b64 exec, exec, s[0:1]
	v_lshl_add_u64 v[12:13], v[14:15], 0, s[38:39]
	v_lshl_add_u64 v[10:11], v[200:201], 0, v[10:11]
	v_min_i32_e32 v18, 0x187, v18
	v_cndmask_b32_e32 v21, v11, v13, vcc
	v_cndmask_b32_e32 v20, v10, v12, vcc
	global_load_dwordx4 v[10:13], v[14:15], off offset:128 nt
	s_nop 0
	global_load_dwordx4 v[14:17], v[14:15], off nt
	s_nop 0
	global_load_dwordx4 v[90:93], v[20:21], off offset:128 nt
	global_load_dwordx4 v[150:153], v[20:21], off nt
	v_ashrrev_i32_e32 v19, 31, v18
	v_lshl_add_u64 v[18:19], v[18:19], 2, s[40:41]
	global_load_dword v233, v[18:19], off
	v_add_u32_e32 v26, -16, v223
	v_mov_b32_e32 v26, v251
	v_cmp_lt_i32_e32 vcc, s19, v26
	v_min_i32_e32 v18, 0x182, v26
	s_nop 0
	v_cndmask_b32_e64 v19, 0, 1, vcc
	v_cmp_gt_i32_e32 vcc, s24, v26
	s_nop 1
	v_cndmask_b32_e32 v19, 2, v19, vcc
	v_mul_i32_i24_e32 v20, 0xffffff7f, v19
	v_lshlrev_b32_e32 v19, 1, v19
	v_add_lshl_u32 v18, v20, v18, v19
	v_sub_u32_e32 v18, s18, v18
	v_cmp_lt_i32_e32 vcc, s25, v18
	v_cmp_gt_i32_e64 s[0:1], s17, v18
	s_and_saveexec_b64 s[14:15], s[0:1]
	s_xor_b64 s[0:1], exec, s[14:15]
	v_ashrrev_i32_e32 v19, 31, v18
	v_lshlrev_b64 v[20:21], 11, v[18:19]
	v_lshl_add_u64 v[22:23], v[194:195], 0, v[20:21]
	s_andn2_saveexec_b64 s[0:1], s[0:1]
	v_add_u32_e32 v19, 0xfffff800, v18
	v_mad_u64_u32 v[22:23], s[14:15], v19, s26, v[198:199]
	v_mov_b32_e32 v19, v157
	v_lshlrev_b64 v[20:21], 11, v[18:19]
	s_or_b64 exec, exec, s[0:1]
	v_lshl_add_u64 v[18:19], v[22:23], 0, s[38:39]
	v_lshl_add_u64 v[20:21], v[200:201], 0, v[20:21]
	v_min_i32_e32 v26, 0x187, v26
	v_cndmask_b32_e32 v29, v21, v19, vcc
	v_cndmask_b32_e32 v28, v20, v18, vcc
	global_load_dwordx4 v[18:21], v[22:23], off offset:128 nt
	s_nop 0
	global_load_dwordx4 v[22:25], v[22:23], off nt
	s_nop 0
	global_load_dwordx4 v[82:85], v[28:29], off offset:128 nt
	global_load_dwordx4 v[98:101], v[28:29], off nt
	v_ashrrev_i32_e32 v27, 31, v26
	v_lshl_add_u64 v[26:27], v[26:27], 2, s[40:41]
	global_load_dword v234, v[26:27], off
	v_add_u32_e32 v70, -8, v223
	v_mov_b32_e32 v70, v252
	v_cmp_lt_i32_e32 vcc, s19, v70
	v_min_i32_e32 v26, 0x182, v70
	s_nop 0
	v_cndmask_b32_e64 v27, 0, 1, vcc
	v_cmp_gt_i32_e32 vcc, s24, v70
	s_nop 1
	v_cndmask_b32_e32 v27, 2, v27, vcc
	v_mul_i32_i24_e32 v28, 0xffffff7f, v27
	v_lshlrev_b32_e32 v27, 1, v27
	v_add_lshl_u32 v26, v28, v26, v27
	v_sub_u32_e32 v26, s18, v26
	v_cmp_lt_i32_e32 vcc, s25, v26
	v_cmp_gt_i32_e64 s[0:1], s17, v26
	s_and_saveexec_b64 s[14:15], s[0:1]
	s_xor_b64 s[0:1], exec, s[14:15]
	v_ashrrev_i32_e32 v27, 31, v26
	v_lshlrev_b64 v[28:29], 11, v[26:27]
	v_lshl_add_u64 v[30:31], v[194:195], 0, v[28:29]
	s_andn2_saveexec_b64 s[0:1], s[0:1]
	v_add_u32_e32 v27, 0xfffff800, v26
	v_mad_u64_u32 v[30:31], s[14:15], v27, s26, v[198:199]
	v_mov_b32_e32 v27, v157
	v_lshlrev_b64 v[28:29], 11, v[26:27]
	s_or_b64 exec, exec, s[0:1]
	v_lshl_add_u64 v[26:27], v[30:31], 0, s[38:39]
	v_lshl_add_u64 v[28:29], v[200:201], 0, v[28:29]
	v_min_i32_e32 v70, 0x187, v70
	v_cndmask_b32_e32 v73, v29, v27, vcc
	v_cndmask_b32_e32 v72, v28, v26, vcc
	global_load_dwordx4 v[26:29], v[30:31], off offset:128 nt
	s_nop 0
	global_load_dwordx4 v[30:33], v[30:31], off nt
	s_nop 0
	global_load_dwordx4 v[106:109], v[72:73], off offset:128 nt
	global_load_dwordx4 v[130:133], v[72:73], off nt
	v_ashrrev_i32_e32 v71, 31, v70
	v_lshl_add_u64 v[70:71], v[70:71], 2, s[40:41]
	global_load_dword v235, v[70:71], off
	v_mov_b32_e32 v254, v253
	v_cmp_lt_i32_e32 vcc, s19, v254
	v_min_i32_e32 v70, 0x182, v254
	s_nop 0
	v_cndmask_b32_e64 v71, 0, 1, vcc
	v_cmp_gt_i32_e32 vcc, s24, v254
	s_nop 1
	v_cndmask_b32_e32 v71, 2, v71, vcc
	v_mul_i32_i24_e32 v72, 0xffffff7f, v71
	v_lshlrev_b32_e32 v71, 1, v71
	v_add_lshl_u32 v70, v72, v70, v71
	v_sub_u32_e32 v72, s18, v70
	v_cmp_lt_i32_e32 vcc, s25, v72
	v_cmp_gt_i32_e64 s[0:1], s17, v72
	s_and_saveexec_b64 s[14:15], s[0:1]
	s_xor_b64 s[0:1], exec, s[14:15]
	v_ashrrev_i32_e32 v73, 31, v72
	v_lshlrev_b64 v[70:71], 11, v[72:73]
	v_lshl_add_u64 v[74:75], v[194:195], 0, v[70:71]
	s_andn2_saveexec_b64 s[0:1], s[0:1]
	v_add_u32_e32 v70, 0xfffff800, v72
	v_mov_b32_e32 v73, v157
	v_mad_u64_u32 v[74:75], s[14:15], v70, s26, v[198:199]
	v_lshlrev_b64 v[70:71], 11, v[72:73]
	s_or_b64 exec, exec, s[0:1]
	v_add_f32_e32 v72, v236, v237
	v_add_f32_e32 v73, v228, v72
	v_max_f32_e32 v72, v225, v225
	v_max_f32_e32 v156, v72, v73
	v_sub_f32_e32 v73, v73, v156
	v_mul_f32_e32 v73, 0x3fb8aa3b, v73
	v_exp_f32_e32 v228, v73
	v_add_f32_e32 v73, v238, v239
	v_add_f32_e32 v73, v227, v73
	v_sub_f32_e32 v72, v225, v156
	v_max_f32_e32 v225, v156, v73
	v_sub_f32_e32 v73, v73, v225
	v_mul_f32_e32 v73, 0x3fb8aa3b, v73
	v_sub_f32_e32 v156, v156, v225
	v_exp_f32_e32 v238, v73
	v_add_f32_e32 v73, v240, v241
	v_mul_f32_e32 v156, 0x3fb8aa3b, v156
	v_add_f32_e32 v73, v226, v73
	v_mul_f32_e32 v72, 0x3fb8aa3b, v72
	v_exp_f32_e32 v236, v156
	v_max_f32_e32 v156, v225, v73
	v_exp_f32_e32 v72, v72
	v_sub_f32_e32 v225, v225, v156
	v_sub_f32_e32 v73, v73, v156
	v_mul_f32_e32 v225, 0x3fb8aa3b, v225
	v_mul_f32_e32 v73, 0x3fb8aa3b, v73
	v_exp_f32_e32 v226, v225
	v_exp_f32_e32 v240, v73
	v_fma_f32 v73, v224, v72, v228
	v_fma_f32 v73, v73, v236, v238
	s_waitcnt vmcnt(30)
; __device__ __forceinline__ void p_attn_sample(const float* P, const float* ck, const float* cv, const float* relb, bf16* heads, const float* sbt, unsigned* qctr, volatile LAS unsigned* slot, int wave, int lane_in) {
;     ...
;         SLOADB(ak0, ak1, av0, av1, ab, 0)
; #pragma unroll 1
;         for (int it0 = 0; it0 < 48; it0 += 8) {
;             SLOADB(bk0, bk1, bv0, bv1, bbv, it0 + 4)
;             SPROCB(ak0, ak1, av0, av1, ab)
;             SLOADB(ak0, ak1, av0, av1, ab, it0 + 8)
;             SPROCB(bk0, bk1, bv0, bv1, bbv)
	v_pk_mul_f32 v[42:43], v[42:43], v[228:229] op_sel_hi:[1,0]
	v_fma_f32 v225, v73, v226, v240
	v_add_f32_e32 v73, v76, v77
	v_add_f32_e32 v73, v222, v73
	v_max_f32_e32 v227, v156, v73
	v_sub_f32_e32 v73, v73, v227
	v_sub_f32_e32 v76, v156, v227
	v_mul_f32_e32 v73, 0x3fb8aa3b, v73
	v_mul_f32_e32 v76, 0x3fb8aa3b, v76
	v_exp_f32_e32 v156, v73
	v_exp_f32_e32 v224, v76
	v_pk_fma_f32 v[42:43], v[220:221], v[72:73], v[42:43] op_sel_hi:[1,0,1]
	v_pk_mul_f32 v[50:51], v[50:51], v[238:239] op_sel_hi:[1,0]
	v_pk_mul_f32 v[6:7], v[6:7], v[156:157] op_sel_hi:[1,0]
	v_pk_fma_f32 v[42:43], v[42:43], v[236:237], v[50:51] op_sel_hi:[1,0,1]
	v_pk_mul_f32 v[50:51], v[58:59], v[240:241] op_sel_hi:[1,0]
	v_pk_mul_f32 v[8:9], v[8:9], v[156:157] op_sel_hi:[1,0]
	v_pk_fma_f32 v[42:43], v[42:43], v[226:227], v[50:51] op_sel_hi:[1,0,1]
	v_pk_mul_f32 v[2:3], v[2:3], v[156:157] op_sel_hi:[1,0]
	v_pk_fma_f32 v[42:43], v[42:43], v[224:225], v[6:7] op_sel_hi:[1,0,1]
	v_pk_mul_f32 v[6:7], v[44:45], v[228:229] op_sel_hi:[1,0]
	v_pk_mul_f32 v[44:45], v[52:53], v[238:239] op_sel_hi:[1,0]
	v_pk_fma_f32 v[6:7], v[218:219], v[72:73], v[6:7] op_sel_hi:[1,0,1]
	v_pk_mul_f32 v[4:5], v[4:5], v[156:157] op_sel_hi:[1,0]
	v_pk_fma_f32 v[6:7], v[6:7], v[236:237], v[44:45] op_sel_hi:[1,0,1]
	v_pk_mul_f32 v[44:45], v[60:61], v[240:241] op_sel_hi:[1,0]
	v_fmac_f32_e32 v156, v225, v224
	v_pk_fma_f32 v[6:7], v[6:7], v[226:227], v[44:45] op_sel_hi:[1,0,1]
	s_add_i32 s3, s3, 8
	v_pk_fma_f32 v[44:45], v[6:7], v[224:225], v[8:9] op_sel_hi:[1,0,1]
	v_pk_mul_f32 v[6:7], v[34:35], v[228:229] op_sel_hi:[1,0]
	v_pk_mul_f32 v[8:9], v[38:39], v[238:239] op_sel_hi:[1,0]
	v_pk_fma_f32 v[6:7], v[214:215], v[72:73], v[6:7] op_sel_hi:[1,0,1]
	v_min_i32_e32 v38, 0x187, v254
	v_pk_fma_f32 v[6:7], v[6:7], v[236:237], v[8:9] op_sel_hi:[1,0,1]
	v_pk_mul_f32 v[8:9], v[46:47], v[240:241] op_sel_hi:[1,0]
	v_ashrrev_i32_e32 v39, 31, v38
	v_pk_fma_f32 v[6:7], v[6:7], v[226:227], v[8:9] op_sel_hi:[1,0,1]
	v_lshl_add_u64 v[38:39], v[38:39], 2, s[40:41]
	v_pk_fma_f32 v[34:35], v[6:7], v[224:225], v[2:3] op_sel_hi:[1,0,1]
	v_pk_mul_f32 v[2:3], v[36:37], v[228:229] op_sel_hi:[1,0]
	v_pk_mul_f32 v[6:7], v[40:41], v[238:239] op_sel_hi:[1,0]
	v_pk_fma_f32 v[2:3], v[216:217], v[72:73], v[2:3] op_sel_hi:[1,0,1]
	v_pk_mul_f32 v[40:41], v[206:207], v[114:115]
	v_pk_fma_f32 v[2:3], v[2:3], v[236:237], v[6:7] op_sel_hi:[1,0,1]
	v_pk_mul_f32 v[6:7], v[48:49], v[240:241] op_sel_hi:[1,0]
	s_cmp_gt_u32 s3, 39
	v_pk_fma_f32 v[2:3], v[2:3], v[226:227], v[6:7] op_sel_hi:[1,0,1]
	v_add_u32_e32 v223, 64, v223
	v_pk_fma_f32 v[36:37], v[2:3], v[224:225], v[4:5] op_sel_hi:[1,0,1]
	v_lshl_add_u64 v[2:3], v[74:75], 0, s[38:39]
	v_lshl_add_u64 v[4:5], v[200:201], 0, v[70:71]
	v_cndmask_b32_e32 v7, v5, v3, vcc
	v_cndmask_b32_e32 v6, v4, v2, vcc
	global_load_dwordx4 v[70:73], v[74:75], off offset:128 nt
	s_nop 0
	global_load_dwordx4 v[74:77], v[74:75], off nt
	s_nop 0
	global_load_dwordx4 v[2:5], v[6:7], off offset:128 nt
	s_nop 0
	global_load_dwordx4 v[6:9], v[6:7], off nt
	s_nop 0
	global_load_dword v222, v[38:39], off
	v_pk_mul_f32 v[38:39], v[208:209], v[116:117]
	s_nop 0
	v_pk_mov_b32 v[46:47], v[40:41], v[38:39] op_sel:[1,0]
	v_mov_b32_e32 v41, v39
	v_pk_add_f32 v[38:39], v[46:47], v[40:41]
	v_pk_mul_f32 v[40:41], v[204:205], v[104:105]
	v_pk_mul_f32 v[46:47], v[202:203], v[102:103]
	v_mov_b32_e32 v48, v40
	v_mov_b32_e32 v49, v46
	v_mov_b32_e32 v46, v41
	v_pk_add_f32 v[40:41], v[48:49], v[46:47]
	v_add_f32_e32 v38, v38, v39
	v_add_f32_e32 v38, v38, v41
	v_add_f32_e32 v38, v40, v38
	s_waitcnt vmcnt(33)
	v_pk_mul_f32 v[46:47], v[208:209], v[124:125]
	v_pk_mul_f32 v[48:49], v[206:207], v[122:123]
	v_add_f32_dpp v38, v38, v38 quad_perm:[1,0,3,2] row_mask:0xf bank_mask:0xf bound_ctrl:1
	v_pk_mov_b32 v[50:51], v[48:49], v[46:47] op_sel:[1,0]
	v_mov_b32_e32 v49, v47
	v_add_f32_dpp v38, v38, v38 quad_perm:[2,3,0,1] row_mask:0xf bank_mask:0xf bound_ctrl:1
	v_pk_add_f32 v[46:47], v[50:51], v[48:49]
	v_pk_mul_f32 v[48:49], v[204:205], v[120:121]
	v_add_f32_dpp v38, v38, v38 row_half_mirror row_mask:0xf bank_mask:0xf bound_ctrl:1
	v_add_f32_e32 v39, v229, v38
	v_max_f32_e32 v41, v227, v39
	v_sub_f32_e32 v39, v39, v41
	v_pk_mul_f32 v[50:51], v[202:203], v[118:119]
	v_mul_f32_e32 v39, 0x3fb8aa3b, v39
	v_mov_b32_e32 v52, v48
	v_mov_b32_e32 v53, v50
	v_mov_b32_e32 v50, v49
	v_exp_f32_e32 v40, v39
	v_pk_add_f32 v[48:49], v[52:53], v[50:51]
	v_add_f32_e32 v39, v46, v47
	v_add_f32_e32 v39, v39, v49
	v_add_f32_e32 v39, v48, v39
	s_waitcnt vmcnt(28)
	v_pk_mul_f32 v[50:51], v[208:209], v[140:141]
	v_pk_mul_f32 v[52:53], v[206:207], v[138:139]
	v_add_f32_dpp v39, v39, v39 quad_perm:[1,0,3,2] row_mask:0xf bank_mask:0xf bound_ctrl:1
	v_pk_mov_b32 v[58:59], v[52:53], v[50:51] op_sel:[1,0]
	v_mov_b32_e32 v53, v51
	v_add_f32_dpp v39, v39, v39 quad_perm:[2,3,0,1] row_mask:0xf bank_mask:0xf bound_ctrl:1
	v_pk_add_f32 v[50:51], v[58:59], v[52:53]
	v_pk_mul_f32 v[52:53], v[204:205], v[136:137]
	v_add_f32_dpp v39, v39, v39 row_half_mirror row_mask:0xf bank_mask:0xf bound_ctrl:1
	v_add_f32_e32 v39, v230, v39
	v_max_f32_e32 v47, v41, v39
	v_sub_f32_e32 v39, v39, v47
	v_pk_mul_f32 v[58:59], v[202:203], v[134:135]
	v_mul_f32_e32 v39, 0x3fb8aa3b, v39
	v_mov_b32_e32 v60, v52
	v_mov_b32_e32 v61, v58
	v_mov_b32_e32 v58, v53
	v_exp_f32_e32 v48, v39
	v_pk_add_f32 v[52:53], v[60:61], v[58:59]
	v_add_f32_e32 v39, v50, v51
	v_add_f32_e32 v39, v39, v53
	v_add_f32_e32 v39, v52, v39
	v_sub_f32_e32 v38, v227, v41
	v_sub_f32_e32 v41, v41, v47
	v_add_f32_dpp v39, v39, v39 quad_perm:[1,0,3,2] row_mask:0xf bank_mask:0xf bound_ctrl:1
	v_mul_f32_e32 v41, 0x3fb8aa3b, v41
	s_waitcnt vmcnt(23)
; __device__ __forceinline__ void p_attn_sample(const float* P, const float* ck, const float* cv, const float* relb, bf16* heads, const float* sbt, unsigned* qctr, volatile LAS unsigned* slot, int wave, int lane_in) {
;     ...
;         SLOADB(ak0, ak1, av0, av1, ab, 0)
; #pragma unroll 1
;         for (int it0 = 0; it0 < 48; it0 += 8) {
;             SLOADB(bk0, bk1, bv0, bv1, bbv, it0 + 4)
;             SPROCB(ak0, ak1, av0, av1, ab)
;             SLOADB(ak0, ak1, av0, av1, ab, it0 + 8)
;             SPROCB(bk0, bk1, bv0, bv1, bbv)
;         }
	v_pk_mul_f32 v[58:59], v[208:209], v[148:149]
	v_add_f32_dpp v39, v39, v39 quad_perm:[2,3,0,1] row_mask:0xf bank_mask:0xf bound_ctrl:1
	v_pk_mul_f32 v[60:61], v[206:207], v[146:147]
	v_exp_f32_e32 v46, v41
	v_add_f32_dpp v39, v39, v39 row_half_mirror row_mask:0xf bank_mask:0xf bound_ctrl:1
	v_add_f32_e32 v39, v231, v39
	v_max_f32_e32 v41, v47, v39
	v_pk_mov_b32 v[102:103], v[60:61], v[58:59] op_sel:[1,0]
	v_mov_b32_e32 v61, v59
	v_sub_f32_e32 v39, v39, v41
	v_pk_add_f32 v[58:59], v[102:103], v[60:61]
	v_pk_mul_f32 v[60:61], v[204:205], v[144:145]
	v_pk_mul_f32 v[102:103], v[202:203], v[142:143]
	v_mul_f32_e32 v39, 0x3fb8aa3b, v39
	v_mov_b32_e32 v104, v60
	v_mov_b32_e32 v105, v102
	v_mov_b32_e32 v102, v61
	v_exp_f32_e32 v52, v39
	v_pk_add_f32 v[60:61], v[104:105], v[102:103]
	v_add_f32_e32 v39, v58, v59
	v_add_f32_e32 v39, v39, v61
	v_add_f32_e32 v39, v60, v39
	v_mul_f32_e32 v38, 0x3fb8aa3b, v38
	v_exp_f32_e32 v38, v38
	v_add_f32_dpp v39, v39, v39 quad_perm:[1,0,3,2] row_mask:0xf bank_mask:0xf bound_ctrl:1
	v_sub_f32_e32 v47, v47, v41
	v_mul_f32_e32 v47, 0x3fb8aa3b, v47
	v_add_f32_dpp v39, v39, v39 quad_perm:[2,3,0,1] row_mask:0xf bank_mask:0xf bound_ctrl:1
	v_exp_f32_e32 v50, v47
	s_nop 0
	v_add_f32_dpp v39, v39, v39 row_half_mirror row_mask:0xf bank_mask:0xf bound_ctrl:1
	s_waitcnt vmcnt(20)
	v_add_f32_e32 v39, v232, v39
	v_max_f32_e32 v225, v41, v39
	v_sub_f32_e32 v39, v39, v225
	v_mul_f32_e32 v39, 0x3fb8aa3b, v39
	v_sub_f32_e32 v41, v41, v225
	v_exp_f32_e32 v60, v39
	v_fma_f32 v39, v156, v38, v40
	v_mul_f32_e32 v41, 0x3fb8aa3b, v41
	v_fma_f32 v39, v39, v46, v48
	v_exp_f32_e32 v58, v41
	v_fma_f32 v39, v39, v50, v52
	v_pk_mul_f32 v[62:63], v[62:63], v[40:41] op_sel_hi:[1,0]
	v_fma_f32 v224, v39, v58, v60
	v_pk_fma_f32 v[42:43], v[42:43], v[38:39], v[62:63] op_sel_hi:[1,0,1]
	v_pk_mul_f32 v[62:63], v[78:79], v[48:49] op_sel_hi:[1,0]
	s_nop 0
	v_pk_fma_f32 v[42:43], v[42:43], v[46:47], v[62:63] op_sel_hi:[1,0,1]
	v_pk_mul_f32 v[62:63], v[94:95], v[52:53] op_sel_hi:[1,0]
	s_nop 0
	v_pk_fma_f32 v[42:43], v[42:43], v[50:51], v[62:63] op_sel_hi:[1,0,1]
	v_pk_mul_f32 v[62:63], v[126:127], v[60:61] op_sel_hi:[1,0]
	s_nop 0
	v_pk_fma_f32 v[220:221], v[42:43], v[58:59], v[62:63] op_sel_hi:[1,0,1]
	v_pk_mul_f32 v[42:43], v[64:65], v[40:41] op_sel_hi:[1,0]
	s_nop 0
	v_pk_fma_f32 v[42:43], v[44:45], v[38:39], v[42:43] op_sel_hi:[1,0,1]
	v_pk_mul_f32 v[44:45], v[80:81], v[48:49] op_sel_hi:[1,0]
	s_nop 0
	v_pk_fma_f32 v[42:43], v[42:43], v[46:47], v[44:45] op_sel_hi:[1,0,1]
	v_pk_mul_f32 v[44:45], v[96:97], v[52:53] op_sel_hi:[1,0]
	s_nop 0
	v_pk_fma_f32 v[42:43], v[42:43], v[50:51], v[44:45] op_sel_hi:[1,0,1]
	v_pk_mul_f32 v[44:45], v[128:129], v[60:61] op_sel_hi:[1,0]
	s_nop 0
	v_pk_fma_f32 v[218:219], v[42:43], v[58:59], v[44:45] op_sel_hi:[1,0,1]
	v_pk_mul_f32 v[42:43], v[54:55], v[40:41] op_sel_hi:[1,0]
	s_nop 0
	v_pk_fma_f32 v[34:35], v[34:35], v[38:39], v[42:43] op_sel_hi:[1,0,1]
	v_pk_mul_f32 v[42:43], v[66:67], v[48:49] op_sel_hi:[1,0]
	s_nop 0
	v_pk_fma_f32 v[34:35], v[34:35], v[46:47], v[42:43] op_sel_hi:[1,0,1]
	v_pk_mul_f32 v[42:43], v[86:87], v[52:53] op_sel_hi:[1,0]
	s_nop 0
	v_pk_fma_f32 v[34:35], v[34:35], v[50:51], v[42:43] op_sel_hi:[1,0,1]
	v_pk_mul_f32 v[42:43], v[110:111], v[60:61] op_sel_hi:[1,0]
	s_nop 0
	v_pk_fma_f32 v[214:215], v[34:35], v[58:59], v[42:43] op_sel_hi:[1,0,1]
	v_pk_mul_f32 v[34:35], v[56:57], v[40:41] op_sel_hi:[1,0]
	s_nop 0
	v_pk_fma_f32 v[34:35], v[36:37], v[38:39], v[34:35] op_sel_hi:[1,0,1]
	v_pk_mul_f32 v[36:37], v[68:69], v[48:49] op_sel_hi:[1,0]
	s_nop 0
	v_pk_fma_f32 v[34:35], v[34:35], v[46:47], v[36:37] op_sel_hi:[1,0,1]
	v_pk_mul_f32 v[36:37], v[88:89], v[52:53] op_sel_hi:[1,0]
	s_nop 0
	v_pk_fma_f32 v[34:35], v[34:35], v[50:51], v[36:37] op_sel_hi:[1,0,1]
	v_pk_mul_f32 v[36:37], v[112:113], v[60:61] op_sel_hi:[1,0]
	s_nop 0
	v_pk_fma_f32 v[216:217], v[34:35], v[58:59], v[36:37] op_sel_hi:[1,0,1]
	s_cbranch_scc1 .LBB0_1285
	s_waitcnt vmcnt(17)
	v_mov_b64_e32 v[34:35], v[90:91]
	s_waitcnt vmcnt(12)
	v_mov_b64_e32 v[38:39], v[82:83]
	s_waitcnt vmcnt(7)
	v_mov_b64_e32 v[46:47], v[106:107]
	v_mov_b64_e32 v[42:43], v[150:151]
	v_mov_b64_e32 v[50:51], v[98:99]
	s_waitcnt vmcnt(6)
	v_mov_b64_e32 v[58:59], v[130:131]
	v_mov_b64_e32 v[36:37], v[92:93]
	v_mov_b64_e32 v[40:41], v[84:85]
	v_mov_b64_e32 v[48:49], v[108:109]
	v_mov_b64_e32 v[44:45], v[152:153]
	v_mov_b64_e32 v[52:53], v[100:101]
	v_mov_b64_e32 v[60:61], v[132:133]
	s_waitcnt vmcnt(5)
	v_mov_b32_e32 v226, v235
	v_mov_b32_e32 v227, v234
	v_mov_b32_e32 v228, v233
	s_branch .LBB0_1251

; __device__ __forceinline__ void p_attn_sample(const float* P, const float* ck, const float* cv, const float* relb, bf16* heads, const float* sbt, unsigned* qctr, volatile LAS unsigned* slot, int wave, int lane_in) {
;     ...
;         __syncthreads(); if (threadIdx.x == 0) *slot = __hip_atomic_fetch_add(qctr, 1u, __ATOMIC_RELAXED, __HIP_MEMORY_SCOPE_AGENT); __syncthreads();
;         const unsigned wt = *slot; if (wt >= (unsigned)(DB * 4)) break;
;         const int b = (int)(wt >> 2), t = wave & 3, h = 2 * (int)(wt & 3u) + (wave >> 2), sr = 4 * b + t, m = MP + sr, p = SEQ + t;
;         f32x4 q0 = *(const f32x4*)(P + (size_t)m * NINP + C_AQ + h * 64 + 8 * c), q1 = *(const f32x4*)(P + (size_t)m * NINP + C_AQ + h * 64 + 8 * c + 4);
;         q0 = q0 * 0.125f; q1 = q1 * 0.125f;
;         const float* knew = P + (size_t)(MP + b * DS) * NINP + C_AK + h * 64 + 8 * c; const float* kold = ck + ((size_t)b * SEQ * NH + h) * HD + 8 * c;
;         const float* vold = cv + ((size_t)b * SEQ * NH + h) * HD + 8 * c;
;         const float* sbh = sbt + h * 392;
;         float mx = -INFINITY, sum = 0.f; float acc[8];
; #pragma unroll
;         for (int j = 0; j < 8; ++j) acc[j] = 0.f;
;         f32x4 ak0[4], ak1[4], av0[4], av1[4], bk0[4], bk1[4], bv0[4], bv1[4]; float ab[4], bbv[4];
;     ...
;         SLOADB(ak0, ak1, av0, av1, ab, 0)
.LBB0_1381:
	s_or_b64 exec, exec, s[0:1]
	v_mov_b32_e32 v2, s34
	s_waitcnt lgkmcnt(0)
	s_barrier
	ds_read_b32 v2, v2
	s_mov_b64 s[0:1], -1
	s_waitcnt lgkmcnt(0)
	v_cmp_lt_u32_e32 vcc, s35, v2
	v_readfirstlane_b32 s3, v2
	s_cbranch_vccnz .LBB0_1376
	s_lshl_b32 s0, s3, 1
	s_and_b32 s31, s3, 0x1fc
	s_and_b32 s0, s0, 6
	s_or_b32 s2, s31, s33
	s_add_i32 s30, s0, s16
	s_mul_i32 s0, s2, 0x3c00
	s_add_u32 s14, s88, s0
	s_addc_u32 s15, s89, 0
	s_lshl_b32 s20, s30, 6
	s_lshl_b64 s[0:1], s[20:21], 2
	s_add_u32 s14, s14, s0
	s_addc_u32 s15, s15, s1
	v_lshlrev_b32_e32 v156, 1, v154
	s_mulk_i32 s31, 0x3c00
	global_load_dwordx4 v[54:57], v156, s[14:15] offset:128
	global_load_dwordx4 v[62:65], v156, s[14:15]
	s_add_u32 s14, s88, s31
	s_addc_u32 s15, s89, 0
	s_add_u32 s0, s14, s0
	s_addc_u32 s1, s15, s1
	s_lshl_b32 s3, s3, 12
	s_and_b32 s3, s3, 0x1fc000
	s_add_i32 s3, s30, s3
	s_lshl_b32 s14, s3, 6
	s_mov_b32 s15, s21
	s_lshl_b64 s[14:15], s[14:15], 2
	v_lshl_add_u64 v[2:3], s[0:1], 0, v[156:157]
	v_lshl_add_u64 v[194:195], v[158:159], 0, s[14:15]
	v_lshl_add_u64 v[196:197], v[2:3], 0, s[24:25]
	v_lshl_add_u64 v[2:3], v[194:195], 0, v[162:163]
	v_lshl_add_u64 v[4:5], v[196:197], 0, v[164:165]
	v_lshl_add_u64 v[198:199], v[160:161], 0, s[14:15]
	v_cndmask_b32_e64 v3, v3, v5, s[6:7]
	v_cndmask_b32_e64 v2, v2, v4, s[6:7]
	v_lshl_add_u64 v[4:5], v[2:3], 0, s[28:29]
	v_lshl_add_u64 v[6:7], v[198:199], 0, v[186:187]
	v_cndmask_b32_e64 v5, v7, v5, s[6:7]
	v_cndmask_b32_e64 v4, v6, v4, s[6:7]
	global_load_dwordx4 v[14:17], v[2:3], off nt
	global_load_dwordx4 v[10:13], v[2:3], off offset:128 nt
	global_load_dwordx4 v[34:37], v[4:5], off offset:128 nt
	global_load_dwordx4 v[42:45], v[4:5], off nt
	v_lshl_add_u64 v[2:3], v[196:197], 0, v[170:171]
	v_lshl_add_u64 v[4:5], v[194:195], 0, v[168:169]
	v_cndmask_b32_e64 v3, v5, v3, s[8:9]
	v_cndmask_b32_e64 v2, v4, v2, s[8:9]
	v_lshl_add_u64 v[4:5], v[2:3], 0, s[28:29]
	v_lshl_add_u64 v[6:7], v[198:199], 0, v[188:189]
	v_cndmask_b32_e64 v5, v7, v5, s[8:9]
	v_cndmask_b32_e64 v4, v6, v4, s[8:9]
	global_load_dwordx4 v[22:25], v[2:3], off nt
	global_load_dwordx4 v[18:21], v[2:3], off offset:128 nt
	global_load_dwordx4 v[38:41], v[4:5], off offset:128 nt
	global_load_dwordx4 v[50:53], v[4:5], off nt
	v_lshl_add_u64 v[2:3], v[196:197], 0, v[176:177]
	v_lshl_add_u64 v[4:5], v[194:195], 0, v[174:175]
	v_cndmask_b32_e64 v3, v5, v3, s[10:11]
	v_cndmask_b32_e64 v2, v4, v2, s[10:11]
	v_lshl_add_u64 v[4:5], v[2:3], 0, s[28:29]
	v_lshl_add_u64 v[6:7], v[198:199], 0, v[190:191]
	s_mulk_i32 s30, 0x188
	s_mov_b32 s31, s21
	v_cndmask_b32_e64 v5, v7, v5, s[10:11]
	v_cndmask_b32_e64 v4, v6, v4, s[10:11]
	s_lshl_b64 s[0:1], s[30:31], 2
	v_readlane_b32 s14, v245, 37
	global_load_dwordx4 v[30:33], v[2:3], off nt
	global_load_dwordx4 v[26:29], v[2:3], off offset:128 nt
	global_load_dwordx4 v[46:49], v[4:5], off offset:128 nt
	global_load_dwordx4 v[58:61], v[4:5], off nt
	v_lshl_add_u64 v[2:3], v[196:197], 0, v[182:183]
	v_lshl_add_u64 v[4:5], v[194:195], 0, v[180:181]
	v_readlane_b32 s15, v245, 38
	s_add_u32 s30, s14, s0
	v_cndmask_b32_e64 v3, v5, v3, s[12:13]
	v_cndmask_b32_e64 v2, v4, v2, s[12:13]
	s_addc_u32 s31, s15, s1
	v_lshl_add_u64 v[4:5], v[2:3], 0, s[28:29]
	v_lshl_add_u64 v[6:7], v[198:199], 0, v[192:193]
	v_lshl_add_u64 v[66:67], v[166:167], 2, s[30:31]
	v_cndmask_b32_e64 v7, v7, v5, s[12:13]
	v_cndmask_b32_e64 v6, v6, v4, s[12:13]
	v_lshl_add_u64 v[68:69], v[172:173], 2, s[30:31]
	v_lshl_add_u64 v[78:79], v[178:179], 2, s[30:31]
	global_load_dwordx4 v[74:77], v[2:3], off nt
	global_load_dwordx4 v[70:73], v[2:3], off offset:128 nt
	s_nop 0
	global_load_dwordx4 v[2:5], v[6:7], off offset:128 nt
	s_nop 0
	global_load_dwordx4 v[6:9], v[6:7], off nt
	v_lshl_add_u64 v[80:81], v[184:185], 2, s[30:31]
	global_load_dword v227, v[66:67], off
	global_load_dword v226, v[68:69], off
	global_load_dword v225, v[78:79], off
	global_load_dword v221, v[80:81], off
	v_mov_b32_e32 v223, 0
	v_mov_b32_e32 v224, 0xff800000
	s_mov_b32 s3, -8
	v_mov_b32_e32 v222, v155
	v_mov_b32_e32 v218, 0
	v_mov_b32_e32 v219, v223
	v_mov_b32_e32 v216, 0
	v_mov_b32_e32 v217, v223
	v_mov_b32_e32 v212, 0
	v_mov_b32_e32 v213, v223
	v_mov_b32_e32 v214, 0
	v_mov_b32_e32 v215, v223
	s_waitcnt vmcnt(0)
	v_pk_mul_f32 v[202:203], v[56:57], s[22:23] op_sel_hi:[1,0]
	v_pk_mul_f32 v[206:207], v[64:65], s[22:23] op_sel_hi:[1,0]
	v_pk_mul_f32 v[204:205], v[62:63], s[22:23] op_sel_hi:[1,0]
	v_pk_mul_f32 v[200:201], v[54:55], s[22:23] op_sel_hi:[1,0]
	v_pk_mov_b32 v[208:209], v[204:205], v[206:207] op_sel:[1,0]
	v_mov_b32_e32 v210, v204
	v_mov_b32_e32 v211, v207
.LBB0_1383:
	v_subrev_u32_e32 v255, 56, v222
	v_min_i32_e32 v255, 0x187, v255
	v_lshl_add_u32 v255, v255, 2, s101
	ds_read_b32 v246, v255
	v_subrev_u32_e32 v255, 48, v222
	v_min_i32_e32 v255, 0x187, v255
	v_lshl_add_u32 v255, v255, 2, s101
	ds_read_b32 v247, v255
	v_subrev_u32_e32 v255, 40, v222
	v_min_i32_e32 v255, 0x187, v255
	v_lshl_add_u32 v255, v255, 2, s101
	ds_read_b32 v248, v255
	v_subrev_u32_e32 v255, 32, v222
	v_min_i32_e32 v255, 0x187, v255
	v_lshl_add_u32 v255, v255, 2, s101
	ds_read_b32 v249, v255
	v_subrev_u32_e32 v255, 24, v222
	v_min_i32_e32 v255, 0x187, v255
	v_lshl_add_u32 v255, v255, 2, s101
	ds_read_b32 v250, v255
	v_subrev_u32_e32 v255, 16, v222
	v_min_i32_e32 v255, 0x187, v255
	v_lshl_add_u32 v255, v255, 2, s101
	ds_read_b32 v251, v255
	v_subrev_u32_e32 v255, 8, v222
	v_min_i32_e32 v255, 0x187, v255
	v_lshl_add_u32 v255, v255, 2, s101
	ds_read_b32 v252, v255
	v_min_i32_e32 v255, 0x187, v222
	v_lshl_add_u32 v255, v255, 2, s101
	ds_read_b32 v253, v255
	s_waitcnt lgkmcnt(0)
	v_subrev_u32_e32 v66, 56, v222
	v_mov_b32_e32 v66, v246
	v_cmp_lt_i32_e32 vcc, s19, v66
	v_min_i32_e32 v54, 0x182, v66
	s_nop 0
	v_cndmask_b32_e64 v55, 0, 1, vcc
	v_cmp_gt_i32_e32 vcc, s23, v66
	s_nop 1
	v_cndmask_b32_e32 v55, 2, v55, vcc
	v_mul_i32_i24_e32 v56, 0xffffff7f, v55
	v_lshlrev_b32_e32 v55, 1, v55
	v_add_lshl_u32 v54, v56, v54, v55
	v_sub_u32_e32 v156, s18, v54
	v_cmp_lt_i32_e32 vcc, s26, v156
	v_cmp_gt_i32_e64 s[0:1], s17, v156
	s_and_saveexec_b64 s[14:15], s[0:1]
	s_xor_b64 s[0:1], exec, s[14:15]
	v_ashrrev_i32_e32 v55, 31, v156
	v_mov_b32_e32 v54, v156
	v_lshlrev_b64 v[56:57], 11, v[54:55]
	v_lshl_add_u64 v[54:55], v[194:195], 0, v[56:57]
	s_andn2_saveexec_b64 s[0:1], s[0:1]
	v_add_u32_e32 v54, 0xfffff800, v156
	v_mad_u64_u32 v[54:55], s[14:15], v54, s27, v[196:197]
	v_lshlrev_b64 v[56:57], 11, v[156:157]
	s_or_b64 exec, exec, s[0:1]
	v_lshl_add_u64 v[62:63], v[54:55], 0, s[28:29]
	v_lshl_add_u64 v[56:57], v[198:199], 0, v[56:57]
	v_cndmask_b32_e32 v63, v57, v63, vcc
	v_cndmask_b32_e32 v62, v56, v62, vcc
	v_min_i32_e32 v66, 0x187, v66
	global_load_dwordx4 v[102:105], v[54:55], off offset:128 nt
	global_load_dwordx4 v[114:117], v[54:55], off nt
	s_nop 0
	global_load_dwordx4 v[54:57], v[62:63], off offset:128 nt
	s_nop 0
	global_load_dwordx4 v[62:65], v[62:63], off nt
	v_ashrrev_i32_e32 v67, 31, v66
	v_lshl_add_u64 v[66:67], v[66:67], 2, s[30:31]
	global_load_dword v228, v[66:67], off
	v_subrev_u32_e32 v82, 48, v222
	v_mov_b32_e32 v82, v247
	v_cmp_lt_i32_e32 vcc, s19, v82
	v_min_i32_e32 v66, 0x182, v82
	s_nop 0
	v_cndmask_b32_e64 v67, 0, 1, vcc
	v_cmp_gt_i32_e32 vcc, s23, v82
	s_nop 1
	v_cndmask_b32_e32 v67, 2, v67, vcc
	v_mul_i32_i24_e32 v68, 0xffffff7f, v67
	v_lshlrev_b32_e32 v67, 1, v67
	v_add_lshl_u32 v66, v68, v66, v67
	v_sub_u32_e32 v68, s18, v66
	v_cmp_lt_i32_e32 vcc, s26, v68
	v_cmp_gt_i32_e64 s[0:1], s17, v68
	s_and_saveexec_b64 s[14:15], s[0:1]
	s_xor_b64 s[0:1], exec, s[14:15]
	v_ashrrev_i32_e32 v69, 31, v68
	v_lshlrev_b64 v[78:79], 11, v[68:69]
	v_lshl_add_u64 v[66:67], v[194:195], 0, v[78:79]
	s_andn2_saveexec_b64 s[0:1], s[0:1]
	v_add_u32_e32 v66, 0xfffff800, v68
	v_mov_b32_e32 v69, v157
	v_mad_u64_u32 v[66:67], s[14:15], v66, s27, v[196:197]
	v_lshlrev_b64 v[78:79], 11, v[68:69]
	s_or_b64 exec, exec, s[0:1]
	v_lshl_add_u64 v[68:69], v[66:67], 0, s[28:29]
	v_lshl_add_u64 v[78:79], v[198:199], 0, v[78:79]
	v_cndmask_b32_e32 v79, v79, v69, vcc
	v_cndmask_b32_e32 v78, v78, v68, vcc
	v_min_i32_e32 v82, 0x187, v82
	global_load_dwordx4 v[118:121], v[66:67], off offset:128 nt
	global_load_dwordx4 v[122:125], v[66:67], off nt
	s_nop 0
	global_load_dwordx4 v[66:69], v[78:79], off offset:128 nt
	s_nop 0
	global_load_dwordx4 v[78:81], v[78:79], off nt
	v_ashrrev_i32_e32 v83, 31, v82
	v_lshl_add_u64 v[82:83], v[82:83], 2, s[30:31]
	global_load_dword v229, v[82:83], off
	v_subrev_u32_e32 v90, 40, v222
	v_mov_b32_e32 v90, v248
	v_cmp_lt_i32_e32 vcc, s19, v90
	v_min_i32_e32 v82, 0x182, v90
	s_nop 0
	v_cndmask_b32_e64 v83, 0, 1, vcc
	v_cmp_gt_i32_e32 vcc, s23, v90
	s_nop 1
	v_cndmask_b32_e32 v83, 2, v83, vcc
	v_mul_i32_i24_e32 v84, 0xffffff7f, v83
	v_lshlrev_b32_e32 v83, 1, v83
	v_add_lshl_u32 v82, v84, v82, v83
	v_sub_u32_e32 v84, s18, v82
	v_cmp_lt_i32_e32 vcc, s26, v84
	v_cmp_gt_i32_e64 s[0:1], s17, v84
	s_and_saveexec_b64 s[14:15], s[0:1]
	s_xor_b64 s[0:1], exec, s[14:15]
	v_ashrrev_i32_e32 v85, 31, v84
	v_lshlrev_b64 v[86:87], 11, v[84:85]
	v_lshl_add_u64 v[82:83], v[194:195], 0, v[86:87]
	s_andn2_saveexec_b64 s[0:1], s[0:1]
	v_add_u32_e32 v82, 0xfffff800, v84
	v_mov_b32_e32 v85, v157
	v_mad_u64_u32 v[82:83], s[14:15], v82, s27, v[196:197]
	v_lshlrev_b64 v[86:87], 11, v[84:85]
	s_or_b64 exec, exec, s[0:1]
	v_lshl_add_u64 v[84:85], v[82:83], 0, s[28:29]
	v_lshl_add_u64 v[86:87], v[198:199], 0, v[86:87]
	v_cndmask_b32_e32 v85, v87, v85, vcc
	v_cndmask_b32_e32 v84, v86, v84, vcc
	global_load_dwordx4 v[134:137], v[82:83], off offset:128 nt
	global_load_dwordx4 v[138:141], v[82:83], off nt
	global_load_dwordx4 v[86:89], v[84:85], off offset:128 nt
	global_load_dwordx4 v[94:97], v[84:85], off nt
	v_min_i32_e32 v82, 0x187, v90
	v_ashrrev_i32_e32 v83, 31, v82
	v_lshl_add_u64 v[82:83], v[82:83], 2, s[30:31]
	global_load_dword v230, v[82:83], off
	v_subrev_u32_e32 v92, 32, v222
	v_mov_b32_e32 v92, v249
	v_cmp_lt_i32_e32 vcc, s19, v92
	v_min_i32_e32 v82, 0x182, v92
	s_nop 0
	v_cndmask_b32_e64 v83, 0, 1, vcc
	v_cmp_gt_i32_e32 vcc, s23, v92
	s_nop 1
	v_cndmask_b32_e32 v83, 2, v83, vcc
	v_mul_i32_i24_e32 v84, 0xffffff7f, v83
	v_lshlrev_b32_e32 v83, 1, v83
	v_add_lshl_u32 v82, v84, v82, v83
	v_sub_u32_e32 v84, s18, v82
	v_cmp_lt_i32_e32 vcc, s26, v84
	v_cmp_gt_i32_e64 s[0:1], s17, v84
	s_and_saveexec_b64 s[14:15], s[0:1]
	s_xor_b64 s[0:1], exec, s[14:15]
	v_ashrrev_i32_e32 v85, 31, v84
	v_lshlrev_b64 v[90:91], 11, v[84:85]
	v_lshl_add_u64 v[82:83], v[194:195], 0, v[90:91]
	s_andn2_saveexec_b64 s[0:1], s[0:1]
	v_add_u32_e32 v82, 0xfffff800, v84
	v_mov_b32_e32 v85, v157
	v_mad_u64_u32 v[82:83], s[14:15], v82, s27, v[196:197]
	v_lshlrev_b64 v[90:91], 11, v[84:85]
	s_or_b64 exec, exec, s[0:1]
	v_lshl_add_u64 v[84:85], v[82:83], 0, s[28:29]
	v_lshl_add_u64 v[90:91], v[198:199], 0, v[90:91]
	v_cndmask_b32_e32 v85, v91, v85, vcc
	v_cndmask_b32_e32 v84, v90, v84, vcc
	global_load_dwordx4 v[142:145], v[82:83], off offset:128 nt
	global_load_dwordx4 v[146:149], v[82:83], off nt
	global_load_dwordx4 v[110:113], v[84:85], off offset:128 nt
	global_load_dwordx4 v[126:129], v[84:85], off nt
	v_min_i32_e32 v82, 0x187, v92
	v_ashrrev_i32_e32 v83, 31, v82
	v_lshl_add_u64 v[82:83], v[82:83], 2, s[30:31]
	global_load_dword v231, v[82:83], off
	v_mov_b32_e32 v82, v15
	v_mov_b32_e32 v15, v17
	v_mov_b32_e32 v83, v16
	v_pk_mul_f32 v[14:15], v[210:211], v[14:15]
	v_pk_mul_f32 v[12:13], v[202:203], v[12:13]
	v_pk_mul_f32 v[10:11], v[200:201], v[10:11]
	v_pk_fma_f32 v[14:15], v[208:209], v[82:83], v[14:15]
	v_mov_b32_e32 v16, v12
	v_mov_b32_e32 v17, v10
	v_mov_b32_e32 v10, v13
	v_pk_add_f32 v[10:11], v[16:17], v[10:11]
	v_add_f32_e32 v12, v14, v15
	v_add_f32_e32 v11, v11, v12
	v_add_f32_e32 v10, v10, v11
	v_mov_b32_e32 v11, v24
	v_pk_mul_f32 v[14:15], v[200:201], v[18:19]
	v_add_f32_dpp v10, v10, v10 quad_perm:[1,0,3,2] row_mask:0xf bank_mask:0xf bound_ctrl:1
	v_mov_b32_e32 v17, v14
	v_subrev_u32_e32 v18, 24, v222
	v_mov_b32_e32 v18, v250
	v_add_f32_dpp v235, v10, v10 quad_perm:[2,3,0,1] row_mask:0xf bank_mask:0xf bound_ctrl:1
	v_mov_b32_e32 v10, v23
	v_mov_b32_e32 v23, v25
	v_pk_mul_f32 v[12:13], v[210:211], v[22:23]
	v_cmp_lt_i32_e32 vcc, s19, v18
	v_pk_fma_f32 v[10:11], v[208:209], v[10:11], v[12:13]
	v_pk_mul_f32 v[12:13], v[202:203], v[20:21]
	v_add_f32_e32 v10, v10, v11
	v_mov_b32_e32 v16, v12
	v_mov_b32_e32 v14, v13
	v_pk_add_f32 v[12:13], v[16:17], v[14:15]
	v_mov_b32_e32 v11, v32
	v_add_f32_e32 v10, v13, v10
	v_add_f32_e32 v10, v12, v10
	v_pk_mul_f32 v[14:15], v[200:201], v[26:27]
	v_mov_b32_e32 v236, 0
	v_add_f32_dpp v10, v10, v10 quad_perm:[1,0,3,2] row_mask:0xf bank_mask:0xf bound_ctrl:1
	v_mov_b32_e32 v17, v14
	v_mov_b32_e32 v238, 0
	v_add_f32_dpp v237, v10, v10 quad_perm:[2,3,0,1] row_mask:0xf bank_mask:0xf bound_ctrl:1
	v_mov_b32_e32 v10, v31
	v_mov_b32_e32 v31, v33
	v_pk_mul_f32 v[12:13], v[210:211], v[30:31]
	v_mov_b32_e32 v240, 0
	v_pk_fma_f32 v[10:11], v[208:209], v[10:11], v[12:13]
	v_pk_mul_f32 v[12:13], v[202:203], v[28:29]
	v_add_f32_e32 v10, v10, v11
	v_mov_b32_e32 v16, v12
	v_mov_b32_e32 v14, v13
	v_pk_add_f32 v[12:13], v[16:17], v[14:15]
	s_waitcnt vmcnt(23)
	v_mov_b32_e32 v11, v76
	v_add_f32_e32 v10, v13, v10
	v_add_f32_e32 v10, v12, v10
	v_pk_mul_f32 v[14:15], v[200:201], v[70:71]
	v_mov_b32_dpp v236, v235 row_half_mirror row_mask:0xf bank_mask:0xf
	v_add_f32_dpp v10, v10, v10 quad_perm:[1,0,3,2] row_mask:0xf bank_mask:0xf bound_ctrl:1
	v_mov_b32_e32 v17, v14
	v_mov_b32_dpp v238, v237 row_half_mirror row_mask:0xf bank_mask:0xf
	v_add_f32_dpp v239, v10, v10 quad_perm:[2,3,0,1] row_mask:0xf bank_mask:0xf bound_ctrl:1
	v_mov_b32_e32 v10, v75
	v_mov_b32_e32 v75, v77
	v_pk_mul_f32 v[12:13], v[210:211], v[74:75]
	v_mov_b32_e32 v77, 0
	v_pk_fma_f32 v[10:11], v[208:209], v[10:11], v[12:13]
	v_pk_mul_f32 v[12:13], v[202:203], v[72:73]
	v_add_f32_e32 v10, v10, v11
	v_mov_b32_e32 v16, v12
	v_mov_b32_e32 v14, v13
	v_pk_add_f32 v[12:13], v[16:17], v[14:15]
	v_cndmask_b32_e64 v11, 0, 1, vcc
	v_add_f32_e32 v10, v13, v10
	v_add_f32_e32 v10, v12, v10
	v_cmp_gt_i32_e32 vcc, s23, v18
	v_mov_b32_dpp v240, v239 row_half_mirror row_mask:0xf bank_mask:0xf
	v_add_f32_dpp v10, v10, v10 quad_perm:[1,0,3,2] row_mask:0xf bank_mask:0xf bound_ctrl:1
	v_cndmask_b32_e32 v11, 2, v11, vcc
	v_mul_i32_i24_e32 v12, 0xffffff7f, v11
	v_add_f32_dpp v76, v10, v10 quad_perm:[2,3,0,1] row_mask:0xf bank_mask:0xf bound_ctrl:1
	v_min_i32_e32 v10, 0x182, v18
	v_lshlrev_b32_e32 v11, 1, v11
	v_add_lshl_u32 v10, v12, v10, v11
	v_sub_u32_e32 v156, s18, v10
	v_mov_b32_dpp v77, v76 row_half_mirror row_mask:0xf bank_mask:0xf
	v_cmp_lt_i32_e32 vcc, s26, v156
	v_cmp_gt_i32_e64 s[0:1], s17, v156
	s_and_saveexec_b64 s[14:15], s[0:1]
	s_xor_b64 s[0:1], exec, s[14:15]
	v_ashrrev_i32_e32 v11, 31, v156
	v_mov_b32_e32 v10, v156
	v_lshlrev_b64 v[10:11], 11, v[10:11]
	v_lshl_add_u64 v[14:15], v[194:195], 0, v[10:11]
	s_andn2_saveexec_b64 s[0:1], s[0:1]
	v_add_u32_e32 v10, 0xfffff800, v156
	v_mad_u64_u32 v[14:15], s[14:15], v10, s27, v[196:197]
	v_lshlrev_b64 v[10:11], 11, v[156:157]
	s_or_b64 exec, exec, s[0:1]
	v_lshl_add_u64 v[12:13], v[14:15], 0, s[28:29]
	v_lshl_add_u64 v[10:11], v[198:199], 0, v[10:11]
	v_min_i32_e32 v18, 0x187, v18
	v_cndmask_b32_e32 v21, v11, v13, vcc
	v_cndmask_b32_e32 v20, v10, v12, vcc
	global_load_dwordx4 v[10:13], v[14:15], off offset:128 nt
	s_nop 0
	global_load_dwordx4 v[14:17], v[14:15], off nt
	s_nop 0
	global_load_dwordx4 v[90:93], v[20:21], off offset:128 nt
	global_load_dwordx4 v[150:153], v[20:21], off nt
	v_ashrrev_i32_e32 v19, 31, v18
	v_lshl_add_u64 v[18:19], v[18:19], 2, s[30:31]
	global_load_dword v232, v[18:19], off
	v_add_u32_e32 v26, -16, v222
	v_mov_b32_e32 v26, v251
	v_cmp_lt_i32_e32 vcc, s19, v26
	v_min_i32_e32 v18, 0x182, v26
	s_nop 0
	v_cndmask_b32_e64 v19, 0, 1, vcc
	v_cmp_gt_i32_e32 vcc, s23, v26
	s_nop 1
	v_cndmask_b32_e32 v19, 2, v19, vcc
	v_mul_i32_i24_e32 v20, 0xffffff7f, v19
; __device__ __forceinline__ void p_attn_sample(const float* P, const float* ck, const float* cv, const float* relb, bf16* heads, const float* sbt, unsigned* qctr, volatile LAS unsigned* slot, int wave, int lane_in) {
;     ...
;         SLOADB(ak0, ak1, av0, av1, ab, 0)
; #pragma unroll 1
;         for (int it0 = 0; it0 < 48; it0 += 8) {
;             SLOADB(bk0, bk1, bv0, bv1, bbv, it0 + 4)
;             SPROCB(ak0, ak1, av0, av1, ab)
;             SLOADB(ak0, ak1, av0, av1, ab, it0 + 8)
;             SPROCB(bk0, bk1, bv0, bv1, bbv)
	v_lshlrev_b32_e32 v19, 1, v19
	v_add_lshl_u32 v18, v20, v18, v19
	v_sub_u32_e32 v18, s18, v18
	v_cmp_lt_i32_e32 vcc, s26, v18
	v_cmp_gt_i32_e64 s[0:1], s17, v18
	s_and_saveexec_b64 s[14:15], s[0:1]
	s_xor_b64 s[0:1], exec, s[14:15]
	v_ashrrev_i32_e32 v19, 31, v18
	v_lshlrev_b64 v[20:21], 11, v[18:19]
	v_lshl_add_u64 v[22:23], v[194:195], 0, v[20:21]
	s_andn2_saveexec_b64 s[0:1], s[0:1]
	v_add_u32_e32 v19, 0xfffff800, v18
	v_mad_u64_u32 v[22:23], s[14:15], v19, s27, v[196:197]
	v_mov_b32_e32 v19, v157
	v_lshlrev_b64 v[20:21], 11, v[18:19]
	s_or_b64 exec, exec, s[0:1]
	v_lshl_add_u64 v[18:19], v[22:23], 0, s[28:29]
	v_lshl_add_u64 v[20:21], v[198:199], 0, v[20:21]
	v_min_i32_e32 v26, 0x187, v26
	v_cndmask_b32_e32 v29, v21, v19, vcc
	v_cndmask_b32_e32 v28, v20, v18, vcc
	global_load_dwordx4 v[18:21], v[22:23], off offset:128 nt
	s_nop 0
	global_load_dwordx4 v[22:25], v[22:23], off nt
	s_nop 0
	global_load_dwordx4 v[82:85], v[28:29], off offset:128 nt
	global_load_dwordx4 v[98:101], v[28:29], off nt
	v_ashrrev_i32_e32 v27, 31, v26
	v_lshl_add_u64 v[26:27], v[26:27], 2, s[30:31]
	global_load_dword v233, v[26:27], off
	v_add_u32_e32 v70, -8, v222
	v_mov_b32_e32 v70, v252
	v_cmp_lt_i32_e32 vcc, s19, v70
	v_min_i32_e32 v26, 0x182, v70
	s_nop 0
	v_cndmask_b32_e64 v27, 0, 1, vcc
	v_cmp_gt_i32_e32 vcc, s23, v70
	s_nop 1
	v_cndmask_b32_e32 v27, 2, v27, vcc
	v_mul_i32_i24_e32 v28, 0xffffff7f, v27
	v_lshlrev_b32_e32 v27, 1, v27
	v_add_lshl_u32 v26, v28, v26, v27
	v_sub_u32_e32 v26, s18, v26
	v_cmp_lt_i32_e32 vcc, s26, v26
	v_cmp_gt_i32_e64 s[0:1], s17, v26
	s_and_saveexec_b64 s[14:15], s[0:1]
	s_xor_b64 s[0:1], exec, s[14:15]
	v_ashrrev_i32_e32 v27, 31, v26
	v_lshlrev_b64 v[28:29], 11, v[26:27]
	v_lshl_add_u64 v[30:31], v[194:195], 0, v[28:29]
	s_andn2_saveexec_b64 s[0:1], s[0:1]
	v_add_u32_e32 v27, 0xfffff800, v26
	v_mad_u64_u32 v[30:31], s[14:15], v27, s27, v[196:197]
	v_mov_b32_e32 v27, v157
	v_lshlrev_b64 v[28:29], 11, v[26:27]
	s_or_b64 exec, exec, s[0:1]
	v_lshl_add_u64 v[26:27], v[30:31], 0, s[28:29]
	v_lshl_add_u64 v[28:29], v[198:199], 0, v[28:29]
	v_min_i32_e32 v70, 0x187, v70
	v_cndmask_b32_e32 v73, v29, v27, vcc
	v_cndmask_b32_e32 v72, v28, v26, vcc
	global_load_dwordx4 v[26:29], v[30:31], off offset:128 nt
	s_nop 0
	global_load_dwordx4 v[30:33], v[30:31], off nt
	s_nop 0
	global_load_dwordx4 v[106:109], v[72:73], off offset:128 nt
	global_load_dwordx4 v[130:133], v[72:73], off nt
	v_ashrrev_i32_e32 v71, 31, v70
	v_lshl_add_u64 v[70:71], v[70:71], 2, s[30:31]
	global_load_dword v234, v[70:71], off
	v_mov_b32_e32 v254, v253
	v_cmp_lt_i32_e32 vcc, s19, v254
	v_min_i32_e32 v70, 0x182, v254
	s_nop 0
	v_cndmask_b32_e64 v71, 0, 1, vcc
	v_cmp_gt_i32_e32 vcc, s23, v254
	s_nop 1
	v_cndmask_b32_e32 v71, 2, v71, vcc
	v_mul_i32_i24_e32 v72, 0xffffff7f, v71
	v_lshlrev_b32_e32 v71, 1, v71
	v_add_lshl_u32 v70, v72, v70, v71
	v_sub_u32_e32 v72, s18, v70
	v_cmp_lt_i32_e32 vcc, s26, v72
	v_cmp_gt_i32_e64 s[0:1], s17, v72
	s_and_saveexec_b64 s[14:15], s[0:1]
	s_xor_b64 s[0:1], exec, s[14:15]
	v_ashrrev_i32_e32 v73, 31, v72
	v_lshlrev_b64 v[70:71], 11, v[72:73]
	v_lshl_add_u64 v[74:75], v[194:195], 0, v[70:71]
	s_andn2_saveexec_b64 s[0:1], s[0:1]
	v_add_u32_e32 v70, 0xfffff800, v72
	v_mov_b32_e32 v73, v157
	v_mad_u64_u32 v[74:75], s[14:15], v70, s27, v[196:197]
	v_lshlrev_b64 v[70:71], 11, v[72:73]
	s_or_b64 exec, exec, s[0:1]
	v_add_f32_e32 v72, v235, v236
	v_add_f32_e32 v73, v227, v72
	v_max_f32_e32 v72, v224, v224
	v_max_f32_e32 v156, v72, v73
	v_sub_f32_e32 v73, v73, v156
	v_mul_f32_e32 v73, 0x3fb8aa3b, v73
	v_sub_f32_e32 v72, v224, v156
	v_exp_f32_e32 v224, v73
	v_add_f32_e32 v73, v237, v238
	v_add_f32_e32 v73, v226, v73
	v_max_f32_e32 v227, v156, v73
	v_sub_f32_e32 v73, v73, v227
	v_mul_f32_e32 v73, 0x3fb8aa3b, v73
	v_sub_f32_e32 v156, v156, v227
	v_exp_f32_e32 v236, v73
	v_add_f32_e32 v73, v239, v240
	v_mul_f32_e32 v156, 0x3fb8aa3b, v156
	v_add_f32_e32 v73, v225, v73
	v_mul_f32_e32 v72, 0x3fb8aa3b, v72
	v_exp_f32_e32 v226, v156
	v_max_f32_e32 v156, v227, v73
	v_exp_f32_e32 v72, v72
	v_sub_f32_e32 v225, v227, v156
	v_sub_f32_e32 v73, v73, v156
	v_mul_f32_e32 v225, 0x3fb8aa3b, v225
	v_mul_f32_e32 v73, 0x3fb8aa3b, v73
	v_exp_f32_e32 v238, v225
	v_exp_f32_e32 v240, v73
	v_fma_f32 v73, v223, v72, v224
	v_fma_f32 v73, v73, v226, v236
	v_pk_mul_f32 v[50:51], v[50:51], v[236:237] op_sel_hi:[1,0]
	v_fma_f32 v223, v73, v238, v240
	v_add_f32_e32 v73, v76, v77
	s_waitcnt vmcnt(35)
	v_add_f32_e32 v73, v221, v73
	v_max_f32_e32 v225, v156, v73
	v_sub_f32_e32 v73, v73, v225
	v_sub_f32_e32 v76, v156, v225
	v_mul_f32_e32 v73, 0x3fb8aa3b, v73
	v_mul_f32_e32 v76, 0x3fb8aa3b, v76
	v_exp_f32_e32 v156, v73
	v_exp_f32_e32 v242, v76
	v_pk_mul_f32 v[42:43], v[42:43], v[224:225] op_sel_hi:[1,0]
	s_add_i32 s3, s3, 8
	v_pk_fma_f32 v[42:43], v[218:219], v[72:73], v[42:43] op_sel_hi:[1,0,1]
	v_pk_mul_f32 v[6:7], v[6:7], v[156:157] op_sel_hi:[1,0]
	v_pk_fma_f32 v[42:43], v[42:43], v[226:227], v[50:51] op_sel_hi:[1,0,1]
	v_pk_mul_f32 v[50:51], v[58:59], v[240:241] op_sel_hi:[1,0]
	v_pk_mul_f32 v[8:9], v[8:9], v[156:157] op_sel_hi:[1,0]
	v_pk_fma_f32 v[42:43], v[42:43], v[238:239], v[50:51] op_sel_hi:[1,0,1]
	v_pk_mul_f32 v[2:3], v[2:3], v[156:157] op_sel_hi:[1,0]
	v_pk_fma_f32 v[42:43], v[42:43], v[242:243], v[6:7] op_sel_hi:[1,0,1]
	v_pk_mul_f32 v[6:7], v[44:45], v[224:225] op_sel_hi:[1,0]
	v_pk_mul_f32 v[44:45], v[52:53], v[236:237] op_sel_hi:[1,0]
	v_pk_fma_f32 v[6:7], v[216:217], v[72:73], v[6:7] op_sel_hi:[1,0,1]
	v_pk_mul_f32 v[4:5], v[4:5], v[156:157] op_sel_hi:[1,0]
	v_pk_fma_f32 v[6:7], v[6:7], v[226:227], v[44:45] op_sel_hi:[1,0,1]
	v_pk_mul_f32 v[44:45], v[60:61], v[240:241] op_sel_hi:[1,0]
	v_fmac_f32_e32 v156, v223, v242
	v_pk_fma_f32 v[6:7], v[6:7], v[238:239], v[44:45] op_sel_hi:[1,0,1]
	s_cmp_gt_u32 s3, 39
	v_pk_fma_f32 v[44:45], v[6:7], v[242:243], v[8:9] op_sel_hi:[1,0,1]
	v_pk_mul_f32 v[6:7], v[34:35], v[224:225] op_sel_hi:[1,0]
	v_pk_mul_f32 v[8:9], v[38:39], v[236:237] op_sel_hi:[1,0]
	v_pk_fma_f32 v[6:7], v[212:213], v[72:73], v[6:7] op_sel_hi:[1,0,1]
	v_min_i32_e32 v38, 0x187, v254
	v_pk_fma_f32 v[6:7], v[6:7], v[226:227], v[8:9] op_sel_hi:[1,0,1]
	v_pk_mul_f32 v[8:9], v[46:47], v[240:241] op_sel_hi:[1,0]
	v_ashrrev_i32_e32 v39, 31, v38
	v_pk_fma_f32 v[6:7], v[6:7], v[238:239], v[8:9] op_sel_hi:[1,0,1]
	v_lshl_add_u64 v[38:39], v[38:39], 2, s[30:31]
	v_pk_fma_f32 v[34:35], v[6:7], v[242:243], v[2:3] op_sel_hi:[1,0,1]
	v_pk_mul_f32 v[2:3], v[36:37], v[224:225] op_sel_hi:[1,0]
	v_pk_mul_f32 v[6:7], v[40:41], v[236:237] op_sel_hi:[1,0]
	v_pk_fma_f32 v[2:3], v[214:215], v[72:73], v[2:3] op_sel_hi:[1,0,1]
	s_waitcnt vmcnt(33)
; __device__ __forceinline__ void p_attn_sample(const float* P, const float* ck, const float* cv, const float* relb, bf16* heads, const float* sbt, unsigned* qctr, volatile LAS unsigned* slot, int wave, int lane_in) {
;     ...
;         SLOADB(ak0, ak1, av0, av1, ab, 0)
; #pragma unroll 1
;         for (int it0 = 0; it0 < 48; it0 += 8) {
;             SLOADB(bk0, bk1, bv0, bv1, bbv, it0 + 4)
;             SPROCB(ak0, ak1, av0, av1, ab)
;             SLOADB(ak0, ak1, av0, av1, ab, it0 + 8)
;             SPROCB(bk0, bk1, bv0, bv1, bbv)
	v_pk_mul_f32 v[40:41], v[204:205], v[114:115]
	v_pk_fma_f32 v[2:3], v[2:3], v[226:227], v[6:7] op_sel_hi:[1,0,1]
	v_pk_mul_f32 v[6:7], v[48:49], v[240:241] op_sel_hi:[1,0]
	v_add_u32_e32 v222, 64, v222
	v_pk_fma_f32 v[2:3], v[2:3], v[238:239], v[6:7] op_sel_hi:[1,0,1]
	s_nop 0
	v_pk_fma_f32 v[36:37], v[2:3], v[242:243], v[4:5] op_sel_hi:[1,0,1]
	v_lshl_add_u64 v[2:3], v[74:75], 0, s[28:29]
	v_lshl_add_u64 v[4:5], v[198:199], 0, v[70:71]
	v_cndmask_b32_e32 v7, v5, v3, vcc
	v_cndmask_b32_e32 v6, v4, v2, vcc
	global_load_dwordx4 v[70:73], v[74:75], off offset:128 nt
	s_nop 0
	global_load_dwordx4 v[74:77], v[74:75], off nt
	s_nop 0
	global_load_dwordx4 v[2:5], v[6:7], off offset:128 nt
	s_nop 0
	global_load_dwordx4 v[6:9], v[6:7], off nt
	s_nop 0
	global_load_dword v221, v[38:39], off
	v_pk_mul_f32 v[38:39], v[206:207], v[116:117]
	s_nop 0
	v_pk_mov_b32 v[46:47], v[40:41], v[38:39] op_sel:[1,0]
	v_mov_b32_e32 v41, v39
	v_pk_add_f32 v[38:39], v[46:47], v[40:41]
	v_pk_mul_f32 v[40:41], v[202:203], v[104:105]
	v_pk_mul_f32 v[46:47], v[200:201], v[102:103]
	v_mov_b32_e32 v48, v40
	v_mov_b32_e32 v49, v46
	v_mov_b32_e32 v46, v41
	v_pk_add_f32 v[40:41], v[48:49], v[46:47]
	v_add_f32_e32 v38, v38, v39
	v_add_f32_e32 v38, v38, v41
	v_add_f32_e32 v38, v40, v38
	s_waitcnt vmcnt(33)
	v_pk_mul_f32 v[46:47], v[206:207], v[124:125]
	v_pk_mul_f32 v[48:49], v[204:205], v[122:123]
	v_add_f32_dpp v38, v38, v38 quad_perm:[1,0,3,2] row_mask:0xf bank_mask:0xf bound_ctrl:1
	v_pk_mov_b32 v[50:51], v[48:49], v[46:47] op_sel:[1,0]
	v_mov_b32_e32 v49, v47
	v_add_f32_dpp v38, v38, v38 quad_perm:[2,3,0,1] row_mask:0xf bank_mask:0xf bound_ctrl:1
	v_pk_add_f32 v[46:47], v[50:51], v[48:49]
	v_pk_mul_f32 v[48:49], v[202:203], v[120:121]
	v_add_f32_dpp v38, v38, v38 row_half_mirror row_mask:0xf bank_mask:0xf bound_ctrl:1
	v_add_f32_e32 v39, v228, v38
	v_max_f32_e32 v41, v225, v39
	v_sub_f32_e32 v39, v39, v41
	v_pk_mul_f32 v[50:51], v[200:201], v[118:119]
	v_mul_f32_e32 v39, 0x3fb8aa3b, v39
	v_mov_b32_e32 v52, v48
	v_mov_b32_e32 v53, v50
	v_mov_b32_e32 v50, v49
	v_exp_f32_e32 v40, v39
	v_pk_add_f32 v[48:49], v[52:53], v[50:51]
	v_add_f32_e32 v39, v46, v47
	v_add_f32_e32 v39, v39, v49
	v_add_f32_e32 v39, v48, v39
	s_waitcnt vmcnt(28)
	v_pk_mul_f32 v[50:51], v[206:207], v[140:141]
	v_pk_mul_f32 v[52:53], v[204:205], v[138:139]
	v_add_f32_dpp v39, v39, v39 quad_perm:[1,0,3,2] row_mask:0xf bank_mask:0xf bound_ctrl:1
	v_pk_mov_b32 v[58:59], v[52:53], v[50:51] op_sel:[1,0]
	v_mov_b32_e32 v53, v51
	v_add_f32_dpp v39, v39, v39 quad_perm:[2,3,0,1] row_mask:0xf bank_mask:0xf bound_ctrl:1
	v_pk_add_f32 v[50:51], v[58:59], v[52:53]
	v_pk_mul_f32 v[52:53], v[202:203], v[136:137]
	v_add_f32_dpp v39, v39, v39 row_half_mirror row_mask:0xf bank_mask:0xf bound_ctrl:1
	v_add_f32_e32 v39, v229, v39
	v_max_f32_e32 v47, v41, v39
	v_sub_f32_e32 v39, v39, v47
	v_pk_mul_f32 v[58:59], v[200:201], v[134:135]
	v_mul_f32_e32 v39, 0x3fb8aa3b, v39
	v_mov_b32_e32 v60, v52
	v_mov_b32_e32 v61, v58
	v_mov_b32_e32 v58, v53
	v_exp_f32_e32 v48, v39
	v_pk_add_f32 v[52:53], v[60:61], v[58:59]
	v_add_f32_e32 v39, v50, v51
	v_add_f32_e32 v39, v39, v53
	v_add_f32_e32 v39, v52, v39
	v_sub_f32_e32 v38, v225, v41
	v_sub_f32_e32 v41, v41, v47
	v_add_f32_dpp v39, v39, v39 quad_perm:[1,0,3,2] row_mask:0xf bank_mask:0xf bound_ctrl:1
	v_mul_f32_e32 v41, 0x3fb8aa3b, v41
	s_waitcnt vmcnt(23)
; __device__ __forceinline__ void p_attn_sample(const float* P, const float* ck, const float* cv, const float* relb, bf16* heads, const float* sbt, unsigned* qctr, volatile LAS unsigned* slot, int wave, int lane_in) {
;     ...
;         SLOADB(ak0, ak1, av0, av1, ab, 0)
; #pragma unroll 1
;         for (int it0 = 0; it0 < 48; it0 += 8) {
;             SLOADB(bk0, bk1, bv0, bv1, bbv, it0 + 4)
;             SPROCB(ak0, ak1, av0, av1, ab)
;             SLOADB(ak0, ak1, av0, av1, ab, it0 + 8)
;             SPROCB(bk0, bk1, bv0, bv1, bbv)
;         }
	v_pk_mul_f32 v[58:59], v[206:207], v[148:149]
	v_add_f32_dpp v39, v39, v39 quad_perm:[2,3,0,1] row_mask:0xf bank_mask:0xf bound_ctrl:1
	v_pk_mul_f32 v[60:61], v[204:205], v[146:147]
	v_exp_f32_e32 v46, v41
	v_add_f32_dpp v39, v39, v39 row_half_mirror row_mask:0xf bank_mask:0xf bound_ctrl:1
	v_add_f32_e32 v39, v230, v39
	v_max_f32_e32 v41, v47, v39
	v_pk_mov_b32 v[102:103], v[60:61], v[58:59] op_sel:[1,0]
	v_mov_b32_e32 v61, v59
	v_sub_f32_e32 v39, v39, v41
	v_pk_add_f32 v[58:59], v[102:103], v[60:61]
	v_pk_mul_f32 v[60:61], v[202:203], v[144:145]
	v_pk_mul_f32 v[102:103], v[200:201], v[142:143]
	v_mul_f32_e32 v39, 0x3fb8aa3b, v39
	v_mov_b32_e32 v104, v60
	v_mov_b32_e32 v105, v102
	v_mov_b32_e32 v102, v61
	v_exp_f32_e32 v52, v39
	v_pk_add_f32 v[60:61], v[104:105], v[102:103]
	v_add_f32_e32 v39, v58, v59
	v_add_f32_e32 v39, v39, v61
	v_add_f32_e32 v39, v60, v39
	v_mul_f32_e32 v38, 0x3fb8aa3b, v38
	v_exp_f32_e32 v38, v38
	v_add_f32_dpp v39, v39, v39 quad_perm:[1,0,3,2] row_mask:0xf bank_mask:0xf bound_ctrl:1
	v_sub_f32_e32 v47, v47, v41
	v_mul_f32_e32 v47, 0x3fb8aa3b, v47
	v_add_f32_dpp v39, v39, v39 quad_perm:[2,3,0,1] row_mask:0xf bank_mask:0xf bound_ctrl:1
	v_exp_f32_e32 v50, v47
	s_nop 0
	v_add_f32_dpp v39, v39, v39 row_half_mirror row_mask:0xf bank_mask:0xf bound_ctrl:1
	s_waitcnt vmcnt(20)
	v_add_f32_e32 v39, v231, v39
	v_max_f32_e32 v224, v41, v39
	v_sub_f32_e32 v39, v39, v224
	v_mul_f32_e32 v39, 0x3fb8aa3b, v39
	v_sub_f32_e32 v41, v41, v224
	v_exp_f32_e32 v60, v39
	v_fma_f32 v39, v156, v38, v40
	v_mul_f32_e32 v41, 0x3fb8aa3b, v41
	v_fma_f32 v39, v39, v46, v48
	v_exp_f32_e32 v58, v41
	v_fma_f32 v39, v39, v50, v52
	v_pk_mul_f32 v[62:63], v[62:63], v[40:41] op_sel_hi:[1,0]
	v_fma_f32 v223, v39, v58, v60
	v_pk_fma_f32 v[42:43], v[42:43], v[38:39], v[62:63] op_sel_hi:[1,0,1]
	v_pk_mul_f32 v[62:63], v[78:79], v[48:49] op_sel_hi:[1,0]
	s_nop 0
	v_pk_fma_f32 v[42:43], v[42:43], v[46:47], v[62:63] op_sel_hi:[1,0,1]
	v_pk_mul_f32 v[62:63], v[94:95], v[52:53] op_sel_hi:[1,0]
	s_nop 0
	v_pk_fma_f32 v[42:43], v[42:43], v[50:51], v[62:63] op_sel_hi:[1,0,1]
	v_pk_mul_f32 v[62:63], v[126:127], v[60:61] op_sel_hi:[1,0]
	s_nop 0
	v_pk_fma_f32 v[218:219], v[42:43], v[58:59], v[62:63] op_sel_hi:[1,0,1]
	v_pk_mul_f32 v[42:43], v[64:65], v[40:41] op_sel_hi:[1,0]
	s_nop 0
	v_pk_fma_f32 v[42:43], v[44:45], v[38:39], v[42:43] op_sel_hi:[1,0,1]
	v_pk_mul_f32 v[44:45], v[80:81], v[48:49] op_sel_hi:[1,0]
	s_nop 0
	v_pk_fma_f32 v[42:43], v[42:43], v[46:47], v[44:45] op_sel_hi:[1,0,1]
	v_pk_mul_f32 v[44:45], v[96:97], v[52:53] op_sel_hi:[1,0]
	s_nop 0
	v_pk_fma_f32 v[42:43], v[42:43], v[50:51], v[44:45] op_sel_hi:[1,0,1]
	v_pk_mul_f32 v[44:45], v[128:129], v[60:61] op_sel_hi:[1,0]
	s_nop 0
	v_pk_fma_f32 v[216:217], v[42:43], v[58:59], v[44:45] op_sel_hi:[1,0,1]
	v_pk_mul_f32 v[42:43], v[54:55], v[40:41] op_sel_hi:[1,0]
	s_nop 0
	v_pk_fma_f32 v[34:35], v[34:35], v[38:39], v[42:43] op_sel_hi:[1,0,1]
	v_pk_mul_f32 v[42:43], v[66:67], v[48:49] op_sel_hi:[1,0]
	s_nop 0
	v_pk_fma_f32 v[34:35], v[34:35], v[46:47], v[42:43] op_sel_hi:[1,0,1]
	v_pk_mul_f32 v[42:43], v[86:87], v[52:53] op_sel_hi:[1,0]
	s_nop 0
	v_pk_fma_f32 v[34:35], v[34:35], v[50:51], v[42:43] op_sel_hi:[1,0,1]
	v_pk_mul_f32 v[42:43], v[110:111], v[60:61] op_sel_hi:[1,0]
	s_nop 0
	v_pk_fma_f32 v[212:213], v[34:35], v[58:59], v[42:43] op_sel_hi:[1,0,1]
	v_pk_mul_f32 v[34:35], v[56:57], v[40:41] op_sel_hi:[1,0]
	s_nop 0
	v_pk_fma_f32 v[34:35], v[36:37], v[38:39], v[34:35] op_sel_hi:[1,0,1]
	v_pk_mul_f32 v[36:37], v[68:69], v[48:49] op_sel_hi:[1,0]
	s_nop 0
	v_pk_fma_f32 v[34:35], v[34:35], v[46:47], v[36:37] op_sel_hi:[1,0,1]
	v_pk_mul_f32 v[36:37], v[88:89], v[52:53] op_sel_hi:[1,0]
	s_nop 0
	v_pk_fma_f32 v[34:35], v[34:35], v[50:51], v[36:37] op_sel_hi:[1,0,1]
	v_pk_mul_f32 v[36:37], v[112:113], v[60:61] op_sel_hi:[1,0]
	s_nop 0
	v_pk_fma_f32 v[214:215], v[34:35], v[58:59], v[36:37] op_sel_hi:[1,0,1]
	s_cbranch_scc1 .LBB0_1417
	s_waitcnt vmcnt(17)
	v_mov_b64_e32 v[34:35], v[90:91]
	s_waitcnt vmcnt(12)
	v_mov_b64_e32 v[38:39], v[82:83]
	s_waitcnt vmcnt(7)
	v_mov_b64_e32 v[46:47], v[106:107]
	v_mov_b64_e32 v[42:43], v[150:151]
	v_mov_b64_e32 v[50:51], v[98:99]
	s_waitcnt vmcnt(6)
	v_mov_b64_e32 v[58:59], v[130:131]
	v_mov_b64_e32 v[36:37], v[92:93]
	v_mov_b64_e32 v[40:41], v[84:85]
	v_mov_b64_e32 v[48:49], v[108:109]
	v_mov_b64_e32 v[44:45], v[152:153]
	v_mov_b64_e32 v[52:53], v[100:101]
	v_mov_b64_e32 v[60:61], v[132:133]
	s_waitcnt vmcnt(5)
	v_mov_b32_e32 v225, v234
	v_mov_b32_e32 v226, v233
	v_mov_b32_e32 v227, v232
	s_branch .LBB0_1383
